# thin row phases: non-temporal hint on the read-once H/Y row loads
# speedup vs baseline: 1.0097x; 1.0067x over previous
.LBB0_663:
	s_cmp_lt_i32 s84, 7
	s_cselect_b64 s[0:1], -1, 0
	s_cmp_gt_i32 s85, 6
	s_cselect_b64 s[2:3], -1, 0
	s_and_b64 s[0:1], s[0:1], s[2:3]
	s_andn2_b64 vcc, exec, s[0:1]
	s_cbranch_vccnz .LBB0_726
	v_mov_b32_e32 v181, 0
	v_lshl_add_u64 v[2:3], s[48:49], 0, v[180:181]
	v_add_co_u32_e32 v4, vcc, 0x2000, v2
	v_lshl_add_u64 v[66:67], s[88:89], 0, v[180:181]
	s_nop 0
	v_addc_co_u32_e32 v5, vcc, 0, v3, vcc
	v_add_co_u32_e32 v6, vcc, 0x4000, v2
	s_mov_b32 s0, 0x934000
	s_nop 0
	v_addc_co_u32_e32 v7, vcc, 0, v3, vcc
	v_add_co_u32_e32 v10, vcc, 0x904000, v66
	global_load_dwordx4 v[2:5], v[4:5], off nt
	s_nop 0
	global_load_dwordx4 v[6:9], v[6:7], off nt
	v_addc_co_u32_e32 v11, vcc, 0, v67, vcc
	v_add_co_u32_e32 v14, vcc, 0x908000, v66
	v_add_u32_e32 v1, 0, v180
	s_nop 0
	v_addc_co_u32_e32 v15, vcc, 0, v67, vcc
	v_add_co_u32_e32 v18, vcc, 0x906000, v66
	global_load_dwordx4 v[10:13], v[10:11], off nt
	s_nop 0
	global_load_dwordx4 v[14:17], v[14:15], off nt
	v_addc_co_u32_e32 v19, vcc, 0, v67, vcc
	v_add_co_u32_e32 v22, vcc, 0x910000, v66
	v_readlane_b32 s1, v250, 21
	s_nop 0
	v_addc_co_u32_e32 v23, vcc, 0, v67, vcc
	v_add_co_u32_e32 v26, vcc, 0x914000, v66
	global_load_dwordx4 v[18:21], v[18:19], off nt
	s_nop 0
	global_load_dwordx4 v[22:25], v[22:23], off nt
	v_addc_co_u32_e32 v27, vcc, 0, v67, vcc
	v_add_co_u32_e32 v30, vcc, 0x912000, v66
	s_waitcnt vmcnt(0)
	v_pk_mul_f32 v[12:13], v[4:5], v[12:13]
	v_addc_co_u32_e32 v31, vcc, 0, v67, vcc
	v_add_co_u32_e32 v34, vcc, 0x91c000, v66
	global_load_dwordx4 v[26:29], v[26:27], off nt
	s_nop 0
	global_load_dwordx4 v[30:33], v[30:31], off nt
	v_addc_co_u32_e32 v35, vcc, 0, v67, vcc
	v_add_co_u32_e32 v38, vcc, 0x920000, v66
	v_pk_mul_f32 v[10:11], v[2:3], v[10:11]
	s_nop 0
	v_addc_co_u32_e32 v39, vcc, 0, v67, vcc
	v_add_co_u32_e32 v42, vcc, 0x91e000, v66
	global_load_dwordx4 v[34:37], v[34:35], off nt
	s_nop 0
	global_load_dwordx4 v[38:41], v[38:39], off nt
	v_addc_co_u32_e32 v43, vcc, 0, v67, vcc
	v_add_co_u32_e32 v46, vcc, 0x928000, v66
	v_pk_add_f32 v[14:15], v[14:15], 1.0 op_sel_hi:[1,0]
	s_nop 0
	v_addc_co_u32_e32 v47, vcc, 0, v67, vcc
	v_add_co_u32_e32 v50, vcc, 0x92c000, v66
	global_load_dwordx4 v[42:45], v[42:43], off nt
	s_nop 0
	global_load_dwordx4 v[46:49], v[46:47], off nt
	v_addc_co_u32_e32 v51, vcc, 0, v67, vcc
	v_add_co_u32_e32 v54, vcc, 0x92a000, v66
	s_nop 1
	v_addc_co_u32_e32 v55, vcc, 0, v67, vcc
	v_add_co_u32_e32 v58, vcc, s0, v66
	global_load_dwordx4 v[50:53], v[50:51], off nt
	s_nop 0
	global_load_dwordx4 v[54:57], v[54:55], off nt
	v_addc_co_u32_e32 v59, vcc, 0, v67, vcc
	s_mov_b32 s0, 0x938000
	v_add_co_u32_e32 v62, vcc, s0, v66
	global_load_dwordx4 v[58:61], v[58:59], off nt
	s_nop 0
	v_addc_co_u32_e32 v63, vcc, 0, v67, vcc
	s_mov_b32 s0, 0x936000
	global_load_dwordx4 v[62:65], v[62:63], off nt
	v_add_co_u32_e32 v66, vcc, s0, v66
	ds_write_b128 v1, v[10:13]
	s_nop 0
	v_addc_co_u32_e32 v67, vcc, 0, v67, vcc
	global_load_dwordx4 v[66:69], v[66:67], off nt
	v_pk_add_f32 v[10:11], v[16:17], 1.0 op_sel_hi:[1,0]
	v_readlane_b32 s0, v250, 44
	v_pk_mul_f32 v[12:13], v[8:9], v[10:11]
	v_pk_mul_f32 v[10:11], v[6:7], v[14:15]
	ds_write_b128 v1, v[10:13] offset:8192
	ds_write_b128 v1, v[18:21] offset:16384
	v_pk_mul_f32 v[12:13], v[4:5], v[24:25]
	v_pk_mul_f32 v[10:11], v[2:3], v[22:23]
	ds_write_b128 v1, v[10:13] offset:24576
	s_lshl_b32 s0, s0, 3
	s_add_i32 s0, s0, s1
	s_cmpk_gt_i32 s0, 0x43ff
	s_waitcnt vmcnt(10)
	v_pk_add_f32 v[10:11], v[28:29], 1.0 op_sel_hi:[1,0]
	v_pk_add_f32 v[14:15], v[26:27], 1.0 op_sel_hi:[1,0]
	v_pk_mul_f32 v[12:13], v[8:9], v[10:11]
	v_pk_mul_f32 v[10:11], v[6:7], v[14:15]
	ds_write_b128 v1, v[10:13] offset:32768
	s_waitcnt vmcnt(9)
	ds_write_b128 v1, v[30:33] offset:40960
	s_waitcnt vmcnt(8)
	v_pk_mul_f32 v[12:13], v[4:5], v[36:37]
	v_pk_mul_f32 v[10:11], v[2:3], v[34:35]
	ds_write_b128 v1, v[10:13] offset:49152
	s_waitcnt vmcnt(7)
	v_pk_add_f32 v[10:11], v[40:41], 1.0 op_sel_hi:[1,0]
	v_pk_add_f32 v[14:15], v[38:39], 1.0 op_sel_hi:[1,0]
	v_pk_mul_f32 v[12:13], v[8:9], v[10:11]
	v_pk_mul_f32 v[10:11], v[6:7], v[14:15]
	ds_write_b128 v1, v[10:13] offset:57344
	v_add_u32_e32 v10, 0x10000, v1
	v_add_u32_e32 v14, 0x12000, v1
	s_waitcnt vmcnt(6)
	ds_write_b128 v10, v[42:45]
	s_waitcnt vmcnt(5)
	v_pk_mul_f32 v[12:13], v[4:5], v[48:49]
	v_pk_mul_f32 v[10:11], v[2:3], v[46:47]
	ds_write_b128 v14, v[10:13]
	s_waitcnt vmcnt(4)
	v_pk_add_f32 v[10:11], v[52:53], 1.0 op_sel_hi:[1,0]
	v_pk_add_f32 v[14:15], v[50:51], 1.0 op_sel_hi:[1,0]
	v_pk_mul_f32 v[12:13], v[8:9], v[10:11]
	v_pk_mul_f32 v[10:11], v[6:7], v[14:15]
	v_add_u32_e32 v14, 0x14000, v1
	ds_write_b128 v14, v[10:13]
	v_add_u32_e32 v10, 0x16000, v1
	s_waitcnt vmcnt(3)
	ds_write_b128 v10, v[54:57]
	s_waitcnt vmcnt(2)
	v_pk_mul_f32 v[4:5], v[4:5], v[60:61]
	v_pk_mul_f32 v[2:3], v[2:3], v[58:59]
	v_add_u32_e32 v10, 0x18000, v1
	ds_write_b128 v10, v[2:5]
	s_waitcnt vmcnt(1)
	v_pk_add_f32 v[2:3], v[64:65], 1.0 op_sel_hi:[1,0]
	v_pk_add_f32 v[10:11], v[62:63], 1.0 op_sel_hi:[1,0]
	v_pk_mul_f32 v[4:5], v[8:9], v[2:3]
	v_pk_mul_f32 v[2:3], v[6:7], v[10:11]
	v_add_u32_e32 v6, 0x1a000, v1
	v_add_u32_e32 v1, 0x1c000, v1
	ds_write_b128 v6, v[2:5]
	s_waitcnt vmcnt(0)
	ds_write_b128 v1, v[66:69]
	s_waitcnt lgkmcnt(0)
	s_barrier
	s_cbranch_scc1 .LBB0_672
	v_mbcnt_lo_u32_b32 v1, -1, 0
	v_mbcnt_hi_u32_b32 v3, -1, v1
	v_and_b32_e32 v1, 64, v3
	v_add_u32_e32 v5, 64, v1
	v_xor_b32_e32 v1, 1, v3
	v_cmp_lt_i32_e32 vcc, v1, v5
	v_xor_b32_e32 v7, 2, v3
	v_lshlrev_b32_e32 v10, 3, v178
	v_cndmask_b32_e32 v1, v3, v1, vcc
	v_cmp_lt_i32_e32 vcc, v7, v5
	v_mov_b32_e32 v11, v181
	v_lshl_add_u64 v[12:13], s[88:89], 0, v[10:11]
	v_cndmask_b32_e32 v7, v3, v7, vcc
	v_lshlrev_b32_e32 v62, 2, v7
	v_xor_b32_e32 v7, 4, v3
	v_cmp_lt_i32_e32 vcc, v7, v5
	s_mov_b64 s[2:3], 0x17d00000
	v_or_b32_e32 v2, 0x100, v178
	v_cndmask_b32_e32 v7, v3, v7, vcc
	v_lshlrev_b32_e32 v63, 2, v7
	v_xor_b32_e32 v7, 8, v3
	v_cmp_lt_i32_e32 vcc, v7, v5
	v_or_b32_e32 v4, 0x140, v178
	v_or_b32_e32 v6, 0x180, v178
	v_cndmask_b32_e32 v7, v3, v7, vcc
	v_lshlrev_b32_e32 v64, 2, v7
	v_xor_b32_e32 v7, 16, v3
	v_cmp_lt_i32_e32 vcc, v7, v5
	v_or_b32_e32 v8, 0x1c0, v178
	v_lshl_add_u64 v[34:35], v[12:13], 0, s[2:3]
	v_cndmask_b32_e32 v7, v3, v7, vcc
	v_lshlrev_b32_e32 v65, 2, v7
	v_xor_b32_e32 v7, 32, v3
	v_cmp_lt_i32_e32 vcc, v7, v5
	v_lshlrev_b32_e32 v12, 4, v178
	v_mov_b32_e32 v13, v181
	v_cndmask_b32_e32 v3, v3, v7, vcc
	s_lshl_b32 s12, s61, 3
	v_lshlrev_b32_e32 v1, 2, v1
	v_lshlrev_b32_e32 v66, 2, v3
	v_lshl_add_u64 v[36:37], s[90:91], 0, v[10:11]
	v_add_u32_e32 v67, 0, v12
	v_lshl_add_u64 v[38:39], s[94:95], 0, v[10:11]
	v_lshl_add_u64 v[40:41], s[88:89], 0, v[12:13]
	v_lshlrev_b32_e32 v68, 4, v178
	v_lshlrev_b32_e32 v69, 4, v2
	v_lshlrev_b32_e32 v70, 4, v4
	v_lshlrev_b32_e32 v71, 4, v6
	v_lshlrev_b32_e32 v72, 4, v8
	s_mov_b32 s13, 0x4b900000
	s_mov_b32 s14, 0x4b901000
	v_mov_b32_e32 v73, 0x358637bd
	s_branch .LBB0_667

.LBB0_667:
	s_mul_hi_i32 s1, s0, 0x78787879
	s_lshr_b32 s2, s1, 31
	s_ashr_i32 s1, s1, 11
	s_add_i32 s4, s1, s2
	s_mul_i32 s1, s4, 0xffffef00
	s_add_i32 s8, s1, s0
	s_cmpk_lt_i32 s8, 0x100
	s_cselect_b64 s[6:7], -1, 0
	s_ashr_i32 s1, s0, 31
	s_lshl_b64 s[2:3], s[0:1], 12
	v_lshl_add_u64 v[42:43], v[34:35], 0, s[2:3]
	global_load_dwordx2 v[58:59], v[42:43], off nt
	global_load_dwordx2 v[56:57], v[42:43], off offset:512 nt
	global_load_dwordx2 v[54:55], v[42:43], off offset:1024 nt
	global_load_dwordx2 v[52:53], v[42:43], off offset:1536 nt
	global_load_dwordx2 v[50:51], v[42:43], off offset:2048 nt
	global_load_dwordx2 v[48:49], v[42:43], off offset:2560 nt
	global_load_dwordx2 v[46:47], v[42:43], off offset:3072 nt
	global_load_dwordx2 v[44:45], v[42:43], off offset:3584 nt
	s_lshl_b64 s[2:3], s[0:1], 11
	s_mov_b64 s[10:11], -1
	s_and_b64 vcc, exec, s[6:7]
	s_cbranch_vccnz .LBB0_669
	v_lshl_add_u64 v[2:3], s[2:3], 1, v[36:37]
	global_load_dwordx2 v[4:5], v[2:3], off nt
	global_load_dwordx2 v[6:7], v[2:3], off offset:512 nt
	global_load_dwordx2 v[8:9], v[2:3], off offset:1024 nt
	global_load_dwordx2 v[10:11], v[2:3], off offset:1536 nt
	global_load_dwordx2 v[12:13], v[2:3], off offset:2048 nt
	global_load_dwordx2 v[60:61], v[2:3], off offset:2560 nt
	global_load_dwordx2 v[74:75], v[2:3], off offset:3072 nt
	global_load_dwordx2 v[76:77], v[2:3], off offset:3584 nt
	s_mov_b64 s[10:11], 0
	s_waitcnt vmcnt(7)
	v_lshlrev_b32_e32 v30, 16, v4
	v_and_b32_e32 v31, 0xffff0000, v4
	v_lshlrev_b32_e32 v32, 16, v5
	v_and_b32_e32 v33, 0xffff0000, v5
	s_waitcnt vmcnt(6)
	v_lshlrev_b32_e32 v26, 16, v6
	v_and_b32_e32 v27, 0xffff0000, v6
	v_lshlrev_b32_e32 v28, 16, v7
	v_and_b32_e32 v29, 0xffff0000, v7
	s_waitcnt vmcnt(5)
	v_lshlrev_b32_e32 v22, 16, v8
	v_and_b32_e32 v23, 0xffff0000, v8
	v_lshlrev_b32_e32 v24, 16, v9
	v_and_b32_e32 v25, 0xffff0000, v9
	s_waitcnt vmcnt(4)
	v_lshlrev_b32_e32 v18, 16, v10
	v_and_b32_e32 v19, 0xffff0000, v10
	v_lshlrev_b32_e32 v20, 16, v11
	v_and_b32_e32 v21, 0xffff0000, v11
	s_waitcnt vmcnt(3)
	v_lshlrev_b32_e32 v14, 16, v12
	v_and_b32_e32 v15, 0xffff0000, v12
	v_lshlrev_b32_e32 v16, 16, v13
	v_and_b32_e32 v17, 0xffff0000, v13
	s_waitcnt vmcnt(2)
	v_lshlrev_b32_e32 v10, 16, v60
	v_and_b32_e32 v11, 0xffff0000, v60
	v_lshlrev_b32_e32 v12, 16, v61
	v_and_b32_e32 v13, 0xffff0000, v61
	s_waitcnt vmcnt(1)
	v_lshlrev_b32_e32 v6, 16, v74
	v_and_b32_e32 v7, 0xffff0000, v74
	v_lshlrev_b32_e32 v8, 16, v75
	v_and_b32_e32 v9, 0xffff0000, v75
	s_waitcnt vmcnt(0)
	v_lshlrev_b32_e32 v2, 16, v76
	v_and_b32_e32 v3, 0xffff0000, v76
	v_lshlrev_b32_e32 v4, 16, v77
	v_and_b32_e32 v5, 0xffff0000, v77
.LBB0_669:
	s_andn2_b64 vcc, exec, s[10:11]
	s_cbranch_vccnz .LBB0_666
	s_ashr_i32 s5, s4, 31
	s_ashr_i32 s9, s8, 31
	s_lshl_b64 s[10:11], s[4:5], 21
	s_add_u32 s1, s64, s10
	s_addc_u32 s5, s65, s11
	s_lshl_b64 s[8:9], s[8:9], 13
	s_add_u32 s8, s1, s8
	s_addc_u32 s9, s5, s9
	global_load_dwordx4 v[30:33], v68, s[8:9] nt
	global_load_dwordx4 v[26:29], v68, s[8:9] offset:1024 nt
	global_load_dwordx4 v[22:25], v68, s[8:9] offset:2048 nt
	global_load_dwordx4 v[18:21], v68, s[8:9] offset:3072 nt
	global_load_dwordx4 v[14:17], v69, s[8:9] nt
	global_load_dwordx4 v[10:13], v70, s[8:9] nt
	global_load_dwordx4 v[6:9], v71, s[8:9] nt
	global_load_dwordx4 v[2:5], v72, s[8:9] nt
	s_mul_i32 s1, s4, 0x1100
	s_sub_i32 s8, s0, s1
	s_ashr_i32 s9, s8, 31
	s_lshl_b64 s[8:9], s[8:9], 13
	s_add_u32 s8, s10, s8
	s_addc_u32 s9, s11, s9
	v_lshl_add_u64 v[60:61], v[40:41], 0, s[8:9]
	s_mov_b64 s[8:9], 0
.LBB0_671:
	v_lshl_add_u64 v[74:75], v[60:61], 0, s[8:9]
	v_add_co_u32_e32 v86, vcc, s13, v74
	s_add_u32 s8, s8, 0x800000
	s_nop 0
	v_addc_co_u32_e32 v87, vcc, 0, v75, vcc
	v_add_co_u32_e32 v102, vcc, s14, v74
	s_addc_u32 s9, s9, 0
	s_nop 0
	v_addc_co_u32_e32 v103, vcc, 0, v75, vcc
	global_load_dwordx4 v[74:77], v[102:103], off offset:-4096 nt
	global_load_dwordx4 v[78:81], v[86:87], off offset:1024 nt
	global_load_dwordx4 v[82:85], v[86:87], off offset:2048 nt
	s_nop 0
	global_load_dwordx4 v[86:89], v[86:87], off offset:3072 nt
	s_nop 0
	global_load_dwordx4 v[90:93], v[102:103], off nt
	global_load_dwordx4 v[94:97], v[102:103], off offset:1024 nt
	global_load_dwordx4 v[98:101], v[102:103], off offset:2048 nt
	s_nop 0
	global_load_dwordx4 v[102:105], v[102:103], off offset:3072 nt
	s_cmp_lg_u32 s8, 0x3800000
	s_waitcnt vmcnt(7)
	v_pk_add_f32 v[32:33], v[32:33], v[76:77]
	v_pk_add_f32 v[30:31], v[30:31], v[74:75]
	s_waitcnt vmcnt(6)
	v_pk_add_f32 v[28:29], v[28:29], v[80:81]
	v_pk_add_f32 v[26:27], v[26:27], v[78:79]
	s_waitcnt vmcnt(5)
	v_pk_add_f32 v[24:25], v[24:25], v[84:85]
	v_pk_add_f32 v[22:23], v[22:23], v[82:83]
	s_waitcnt vmcnt(4)
	v_pk_add_f32 v[20:21], v[20:21], v[88:89]
	v_pk_add_f32 v[18:19], v[18:19], v[86:87]
	s_waitcnt vmcnt(3)
	v_pk_add_f32 v[16:17], v[16:17], v[92:93]
	v_pk_add_f32 v[14:15], v[14:15], v[90:91]
	s_waitcnt vmcnt(2)
	v_pk_add_f32 v[12:13], v[12:13], v[96:97]
	v_pk_add_f32 v[10:11], v[10:11], v[94:95]
	s_waitcnt vmcnt(1)
	v_pk_add_f32 v[8:9], v[8:9], v[100:101]
	v_pk_add_f32 v[6:7], v[6:7], v[98:99]
	s_waitcnt vmcnt(0)
	v_pk_add_f32 v[4:5], v[4:5], v[104:105]
	v_pk_add_f32 v[2:3], v[2:3], v[102:103]
	s_cbranch_scc1 .LBB0_671
	s_branch .LBB0_666

.LBB0_962:
	s_cmp_lt_i32 s84, 10
	s_cselect_b64 s[0:1], -1, 0
	s_cmp_gt_i32 s85, 9
	s_cselect_b64 s[2:3], -1, 0
	s_and_b64 s[0:1], s[0:1], s[2:3]
	s_andn2_b64 vcc, exec, s[0:1]
	s_cbranch_vccnz .LBB0_1025
	v_mov_b32_e32 v181, 0
	v_lshl_add_u64 v[2:3], s[48:49], 0, v[180:181]
	v_add_co_u32_e32 v4, vcc, 0x6000, v2
	v_lshl_add_u64 v[66:67], s[88:89], 0, v[180:181]
	s_nop 0
	v_addc_co_u32_e32 v5, vcc, 0, v3, vcc
	v_add_co_u32_e32 v6, vcc, 0x8000, v2
	s_mov_b32 s0, 0x93a000
	s_nop 0
	v_addc_co_u32_e32 v7, vcc, 0, v3, vcc
	v_add_co_u32_e32 v10, vcc, 0x90a000, v66
	global_load_dwordx4 v[2:5], v[4:5], off nt
	s_nop 0
	global_load_dwordx4 v[6:9], v[6:7], off nt
	v_addc_co_u32_e32 v11, vcc, 0, v67, vcc
	v_add_co_u32_e32 v14, vcc, 0x93e000, v66
	v_add_u32_e32 v1, 0, v180
	s_nop 0
	v_addc_co_u32_e32 v15, vcc, 0, v67, vcc
	v_add_co_u32_e32 v18, vcc, 0x93c000, v66
	global_load_dwordx4 v[10:13], v[10:11], off nt
	s_nop 0
	global_load_dwordx4 v[14:17], v[14:15], off nt
	v_addc_co_u32_e32 v19, vcc, 0, v67, vcc
	v_add_co_u32_e32 v22, vcc, 0x916000, v66
	v_readlane_b32 s1, v250, 21
	s_nop 0
	v_addc_co_u32_e32 v23, vcc, 0, v67, vcc
	v_add_co_u32_e32 v26, vcc, 0x94a000, v66
	global_load_dwordx4 v[18:21], v[18:19], off nt
	s_nop 0
	global_load_dwordx4 v[22:25], v[22:23], off nt
	v_addc_co_u32_e32 v27, vcc, 0, v67, vcc
	v_add_co_u32_e32 v30, vcc, 0x948000, v66
	s_waitcnt vmcnt(0)
	v_pk_mul_f32 v[12:13], v[4:5], v[12:13]
	v_addc_co_u32_e32 v31, vcc, 0, v67, vcc
	v_add_co_u32_e32 v34, vcc, 0x922000, v66
	global_load_dwordx4 v[26:29], v[26:27], off nt
	s_nop 0
	global_load_dwordx4 v[30:33], v[30:31], off nt
	v_addc_co_u32_e32 v35, vcc, 0, v67, vcc
	v_add_co_u32_e32 v38, vcc, 0x956000, v66
	v_pk_mul_f32 v[10:11], v[2:3], v[10:11]
	s_nop 0
	v_addc_co_u32_e32 v39, vcc, 0, v67, vcc
	v_add_co_u32_e32 v42, vcc, 0x954000, v66
	global_load_dwordx4 v[34:37], v[34:35], off nt
	s_nop 0
	global_load_dwordx4 v[38:41], v[38:39], off nt
	v_addc_co_u32_e32 v43, vcc, 0, v67, vcc
	v_add_co_u32_e32 v46, vcc, 0x92e000, v66
	v_pk_add_f32 v[14:15], v[14:15], 1.0 op_sel_hi:[1,0]
	s_nop 0
	v_addc_co_u32_e32 v47, vcc, 0, v67, vcc
	v_add_co_u32_e32 v50, vcc, 0x962000, v66
	global_load_dwordx4 v[42:45], v[42:43], off nt
	s_nop 0
	global_load_dwordx4 v[46:49], v[46:47], off nt
	v_addc_co_u32_e32 v51, vcc, 0, v67, vcc
	v_add_co_u32_e32 v54, vcc, 0x960000, v66
	s_nop 1
	v_addc_co_u32_e32 v55, vcc, 0, v67, vcc
	v_add_co_u32_e32 v58, vcc, s0, v66
	global_load_dwordx4 v[50:53], v[50:51], off nt
	s_nop 0
	global_load_dwordx4 v[54:57], v[54:55], off nt
	v_addc_co_u32_e32 v59, vcc, 0, v67, vcc
	s_mov_b32 s0, 0x96e000
	v_add_co_u32_e32 v62, vcc, s0, v66
	global_load_dwordx4 v[58:61], v[58:59], off nt
	s_nop 0
	v_addc_co_u32_e32 v63, vcc, 0, v67, vcc
	s_mov_b32 s0, 0x96c000
	global_load_dwordx4 v[62:65], v[62:63], off nt
	v_add_co_u32_e32 v66, vcc, s0, v66
	ds_write_b128 v1, v[10:13]
	s_nop 0
	v_addc_co_u32_e32 v67, vcc, 0, v67, vcc
	global_load_dwordx4 v[66:69], v[66:67], off nt
	v_pk_add_f32 v[10:11], v[16:17], 1.0 op_sel_hi:[1,0]
	v_readlane_b32 s0, v250, 44
	v_pk_mul_f32 v[12:13], v[8:9], v[10:11]
	v_pk_mul_f32 v[10:11], v[6:7], v[14:15]
	ds_write_b128 v1, v[10:13] offset:8192
	ds_write_b128 v1, v[18:21] offset:16384
	v_pk_mul_f32 v[12:13], v[4:5], v[24:25]
	v_pk_mul_f32 v[10:11], v[2:3], v[22:23]
	ds_write_b128 v1, v[10:13] offset:24576
	s_lshl_b32 s0, s0, 3
	s_add_i32 s0, s0, s1
	s_cmpk_gt_i32 s0, 0x43ff
	s_waitcnt vmcnt(10)
	v_pk_add_f32 v[10:11], v[28:29], 1.0 op_sel_hi:[1,0]
	v_pk_add_f32 v[14:15], v[26:27], 1.0 op_sel_hi:[1,0]
	v_pk_mul_f32 v[12:13], v[8:9], v[10:11]
	v_pk_mul_f32 v[10:11], v[6:7], v[14:15]
	ds_write_b128 v1, v[10:13] offset:32768
	s_waitcnt vmcnt(9)
	ds_write_b128 v1, v[30:33] offset:40960
	s_waitcnt vmcnt(8)
	v_pk_mul_f32 v[12:13], v[4:5], v[36:37]
	v_pk_mul_f32 v[10:11], v[2:3], v[34:35]
	ds_write_b128 v1, v[10:13] offset:49152
	s_waitcnt vmcnt(7)
	v_pk_add_f32 v[10:11], v[40:41], 1.0 op_sel_hi:[1,0]
	v_pk_add_f32 v[14:15], v[38:39], 1.0 op_sel_hi:[1,0]
	v_pk_mul_f32 v[12:13], v[8:9], v[10:11]
	v_pk_mul_f32 v[10:11], v[6:7], v[14:15]
	ds_write_b128 v1, v[10:13] offset:57344
	v_add_u32_e32 v10, 0x10000, v1
	v_add_u32_e32 v14, 0x12000, v1
	s_waitcnt vmcnt(6)
	ds_write_b128 v10, v[42:45]
	s_waitcnt vmcnt(5)
	v_pk_mul_f32 v[12:13], v[4:5], v[48:49]
	v_pk_mul_f32 v[10:11], v[2:3], v[46:47]
	ds_write_b128 v14, v[10:13]
	s_waitcnt vmcnt(4)
	v_pk_add_f32 v[10:11], v[52:53], 1.0 op_sel_hi:[1,0]
	v_pk_add_f32 v[14:15], v[50:51], 1.0 op_sel_hi:[1,0]
	v_pk_mul_f32 v[12:13], v[8:9], v[10:11]
	v_pk_mul_f32 v[10:11], v[6:7], v[14:15]
	v_add_u32_e32 v14, 0x14000, v1
	ds_write_b128 v14, v[10:13]
	v_add_u32_e32 v10, 0x16000, v1
	s_waitcnt vmcnt(3)
	ds_write_b128 v10, v[54:57]
	s_waitcnt vmcnt(2)
	v_pk_mul_f32 v[4:5], v[4:5], v[60:61]
	v_pk_mul_f32 v[2:3], v[2:3], v[58:59]
	v_add_u32_e32 v10, 0x18000, v1
	ds_write_b128 v10, v[2:5]
	s_waitcnt vmcnt(1)
	v_pk_add_f32 v[2:3], v[64:65], 1.0 op_sel_hi:[1,0]
	v_pk_add_f32 v[10:11], v[62:63], 1.0 op_sel_hi:[1,0]
	v_pk_mul_f32 v[4:5], v[8:9], v[2:3]
	v_pk_mul_f32 v[2:3], v[6:7], v[10:11]
	v_add_u32_e32 v6, 0x1a000, v1
	v_add_u32_e32 v1, 0x1c000, v1
	ds_write_b128 v6, v[2:5]
	s_waitcnt vmcnt(0)
	ds_write_b128 v1, v[66:69]
	s_waitcnt lgkmcnt(0)
	s_barrier
	s_cbranch_scc1 .LBB0_971
	v_mbcnt_lo_u32_b32 v1, -1, 0
	v_mbcnt_hi_u32_b32 v3, -1, v1
	v_and_b32_e32 v1, 64, v3
	v_add_u32_e32 v5, 64, v1
	v_xor_b32_e32 v1, 1, v3
	v_cmp_lt_i32_e32 vcc, v1, v5
	v_xor_b32_e32 v7, 2, v3
	v_lshlrev_b32_e32 v10, 3, v178
	v_cndmask_b32_e32 v1, v3, v1, vcc
	v_cmp_lt_i32_e32 vcc, v7, v5
	v_mov_b32_e32 v11, v181
	v_lshl_add_u64 v[12:13], s[88:89], 0, v[10:11]
	v_cndmask_b32_e32 v7, v3, v7, vcc
	v_lshlrev_b32_e32 v62, 2, v7
	v_xor_b32_e32 v7, 4, v3
	v_cmp_lt_i32_e32 vcc, v7, v5
	s_mov_b64 s[2:3], 0x17d00000
	v_or_b32_e32 v2, 0x100, v178
	v_cndmask_b32_e32 v7, v3, v7, vcc
	v_lshlrev_b32_e32 v63, 2, v7
	v_xor_b32_e32 v7, 8, v3
	v_cmp_lt_i32_e32 vcc, v7, v5
	v_or_b32_e32 v4, 0x140, v178
	v_or_b32_e32 v6, 0x180, v178
	v_cndmask_b32_e32 v7, v3, v7, vcc
	v_lshlrev_b32_e32 v64, 2, v7
	v_xor_b32_e32 v7, 16, v3
	v_cmp_lt_i32_e32 vcc, v7, v5
	v_or_b32_e32 v8, 0x1c0, v178
	v_lshl_add_u64 v[34:35], v[12:13], 0, s[2:3]
	v_cndmask_b32_e32 v7, v3, v7, vcc
	v_lshlrev_b32_e32 v65, 2, v7
	v_xor_b32_e32 v7, 32, v3
	v_cmp_lt_i32_e32 vcc, v7, v5
	v_lshlrev_b32_e32 v12, 4, v178
	v_mov_b32_e32 v13, v181
	v_cndmask_b32_e32 v3, v3, v7, vcc
	s_lshl_b32 s12, s61, 3
	v_lshlrev_b32_e32 v1, 2, v1
	v_lshlrev_b32_e32 v66, 2, v3
	v_lshl_add_u64 v[36:37], s[90:91], 0, v[10:11]
	v_add_u32_e32 v67, 0, v12
	v_lshl_add_u64 v[38:39], s[94:95], 0, v[10:11]
	v_lshl_add_u64 v[40:41], s[88:89], 0, v[12:13]
	v_lshlrev_b32_e32 v68, 4, v178
	v_lshlrev_b32_e32 v69, 4, v2
	v_lshlrev_b32_e32 v70, 4, v4
	v_lshlrev_b32_e32 v71, 4, v6
	v_lshlrev_b32_e32 v72, 4, v8
	s_mov_b32 s13, 0x4b900000
	s_mov_b32 s14, 0x4b901000
	v_mov_b32_e32 v73, 0x358637bd
	s_branch .LBB0_966

.LBB0_970:
	v_lshl_add_u64 v[74:75], v[60:61], 0, s[8:9]
	v_add_co_u32_e32 v86, vcc, s13, v74
	s_add_u32 s8, s8, 0x800000
	s_nop 0
	v_addc_co_u32_e32 v87, vcc, 0, v75, vcc
	v_add_co_u32_e32 v102, vcc, s14, v74
	s_addc_u32 s9, s9, 0
	s_nop 0
	v_addc_co_u32_e32 v103, vcc, 0, v75, vcc
	global_load_dwordx4 v[74:77], v[102:103], off offset:-4096 nt
	global_load_dwordx4 v[78:81], v[86:87], off offset:1024 nt
	global_load_dwordx4 v[82:85], v[86:87], off offset:2048 nt
	s_nop 0
	global_load_dwordx4 v[86:89], v[86:87], off offset:3072 nt
	s_nop 0
	global_load_dwordx4 v[90:93], v[102:103], off nt
	global_load_dwordx4 v[94:97], v[102:103], off offset:1024 nt
	global_load_dwordx4 v[98:101], v[102:103], off offset:2048 nt
	s_nop 0
	global_load_dwordx4 v[102:105], v[102:103], off offset:3072 nt
	s_cmp_lg_u32 s8, 0x1800000
	s_waitcnt vmcnt(7)
	v_pk_add_f32 v[32:33], v[32:33], v[76:77]
	v_pk_add_f32 v[30:31], v[30:31], v[74:75]
	s_waitcnt vmcnt(6)
	v_pk_add_f32 v[28:29], v[28:29], v[80:81]
	v_pk_add_f32 v[26:27], v[26:27], v[78:79]
	s_waitcnt vmcnt(5)
	v_pk_add_f32 v[24:25], v[24:25], v[84:85]
	v_pk_add_f32 v[22:23], v[22:23], v[82:83]
	s_waitcnt vmcnt(4)
	v_pk_add_f32 v[20:21], v[20:21], v[88:89]
	v_pk_add_f32 v[18:19], v[18:19], v[86:87]
	s_waitcnt vmcnt(3)
	v_pk_add_f32 v[16:17], v[16:17], v[92:93]
	v_pk_add_f32 v[14:15], v[14:15], v[90:91]
	s_waitcnt vmcnt(2)
	v_pk_add_f32 v[12:13], v[12:13], v[96:97]
	v_pk_add_f32 v[10:11], v[10:11], v[94:95]
	s_waitcnt vmcnt(1)
	v_pk_add_f32 v[8:9], v[8:9], v[100:101]
	v_pk_add_f32 v[6:7], v[6:7], v[98:99]
	s_waitcnt vmcnt(0)
	v_pk_add_f32 v[4:5], v[4:5], v[104:105]
	v_pk_add_f32 v[2:3], v[2:3], v[102:103]
	s_cbranch_scc1 .LBB0_970
	s_branch .LBB0_965

.LBB0_1564:
	s_cmp_lt_i32 s84, 15
	s_cselect_b64 s[0:1], -1, 0
	s_cmp_gt_i32 s85, 14
	s_cselect_b64 s[2:3], -1, 0
	s_and_b64 s[0:1], s[0:1], s[2:3]
	s_andn2_b64 vcc, exec, s[0:1]
	s_cbranch_vccnz .LBB0_1627
	v_mov_b32_e32 v181, 0
	v_lshl_add_u64 v[2:3], s[48:49], 0, v[180:181]
	v_add_co_u32_e32 v4, vcc, 0xa000, v2
	v_lshl_add_u64 v[66:67], s[88:89], 0, v[180:181]
	s_nop 0
	v_addc_co_u32_e32 v5, vcc, 0, v3, vcc
	v_add_co_u32_e32 v6, vcc, 0xc000, v2
	s_mov_b32 s0, 0x970000
	s_nop 0
	v_addc_co_u32_e32 v7, vcc, 0, v3, vcc
	v_add_co_u32_e32 v10, vcc, 0x940000, v66
	global_load_dwordx4 v[2:5], v[4:5], off nt
	s_nop 0
	global_load_dwordx4 v[6:9], v[6:7], off nt
	v_addc_co_u32_e32 v11, vcc, 0, v67, vcc
	v_add_co_u32_e32 v14, vcc, 0x944000, v66
	v_add_u32_e32 v1, 0, v180
	s_nop 0
	v_addc_co_u32_e32 v15, vcc, 0, v67, vcc
	v_add_co_u32_e32 v18, vcc, 0x942000, v66
	global_load_dwordx4 v[10:13], v[10:11], off nt
	s_nop 0
	global_load_dwordx4 v[14:17], v[14:15], off nt
	v_addc_co_u32_e32 v19, vcc, 0, v67, vcc
	v_add_co_u32_e32 v22, vcc, 0x94c000, v66
	v_readlane_b32 s1, v250, 21
	s_nop 0
	v_addc_co_u32_e32 v23, vcc, 0, v67, vcc
	v_add_co_u32_e32 v26, vcc, 0x950000, v66
	global_load_dwordx4 v[18:21], v[18:19], off nt
	s_nop 0
	global_load_dwordx4 v[22:25], v[22:23], off nt
	v_addc_co_u32_e32 v27, vcc, 0, v67, vcc
	v_add_co_u32_e32 v30, vcc, 0x94e000, v66
	s_waitcnt vmcnt(0)
	v_pk_mul_f32 v[12:13], v[4:5], v[12:13]
	v_addc_co_u32_e32 v31, vcc, 0, v67, vcc
	v_add_co_u32_e32 v34, vcc, 0x958000, v66
	global_load_dwordx4 v[26:29], v[26:27], off nt
	s_nop 0
	global_load_dwordx4 v[30:33], v[30:31], off nt
	v_addc_co_u32_e32 v35, vcc, 0, v67, vcc
	v_add_co_u32_e32 v38, vcc, 0x95c000, v66
	v_pk_mul_f32 v[10:11], v[2:3], v[10:11]
	s_nop 0
	v_addc_co_u32_e32 v39, vcc, 0, v67, vcc
	v_add_co_u32_e32 v42, vcc, 0x95a000, v66
	global_load_dwordx4 v[34:37], v[34:35], off nt
	s_nop 0
	global_load_dwordx4 v[38:41], v[38:39], off nt
	v_addc_co_u32_e32 v43, vcc, 0, v67, vcc
	v_add_co_u32_e32 v46, vcc, 0x964000, v66
	v_pk_add_f32 v[14:15], v[14:15], 1.0 op_sel_hi:[1,0]
	s_nop 0
	v_addc_co_u32_e32 v47, vcc, 0, v67, vcc
	v_add_co_u32_e32 v50, vcc, 0x968000, v66
	global_load_dwordx4 v[42:45], v[42:43], off nt
	s_nop 0
	global_load_dwordx4 v[46:49], v[46:47], off nt
	v_addc_co_u32_e32 v51, vcc, 0, v67, vcc
	v_add_co_u32_e32 v54, vcc, 0x966000, v66
	s_nop 1
	v_addc_co_u32_e32 v55, vcc, 0, v67, vcc
	v_add_co_u32_e32 v58, vcc, s0, v66
	global_load_dwordx4 v[50:53], v[50:51], off nt
	s_nop 0
	global_load_dwordx4 v[54:57], v[54:55], off nt
	v_addc_co_u32_e32 v59, vcc, 0, v67, vcc
	s_mov_b32 s0, 0x974000
	v_add_co_u32_e32 v62, vcc, s0, v66
	global_load_dwordx4 v[58:61], v[58:59], off nt
	s_nop 0
	v_addc_co_u32_e32 v63, vcc, 0, v67, vcc
	s_mov_b32 s0, 0x972000
	global_load_dwordx4 v[62:65], v[62:63], off nt
	v_add_co_u32_e32 v66, vcc, s0, v66
	ds_write_b128 v1, v[10:13]
	s_nop 0
	v_addc_co_u32_e32 v67, vcc, 0, v67, vcc
	global_load_dwordx4 v[66:69], v[66:67], off nt
	v_pk_add_f32 v[10:11], v[16:17], 1.0 op_sel_hi:[1,0]
	v_readlane_b32 s0, v250, 44
	v_pk_mul_f32 v[12:13], v[8:9], v[10:11]
	v_pk_mul_f32 v[10:11], v[6:7], v[14:15]
	ds_write_b128 v1, v[10:13] offset:8192
	ds_write_b128 v1, v[18:21] offset:16384
	v_pk_mul_f32 v[12:13], v[4:5], v[24:25]
	v_pk_mul_f32 v[10:11], v[2:3], v[22:23]
	ds_write_b128 v1, v[10:13] offset:24576
	s_lshl_b32 s0, s0, 3
	s_add_i32 s0, s0, s1
	s_cmpk_gt_i32 s0, 0x43ff
	s_waitcnt vmcnt(0)
	v_pk_add_f32 v[10:11], v[28:29], 1.0 op_sel_hi:[1,0]
	v_pk_add_f32 v[14:15], v[26:27], 1.0 op_sel_hi:[1,0]
	v_pk_mul_f32 v[12:13], v[8:9], v[10:11]
	v_pk_mul_f32 v[10:11], v[6:7], v[14:15]
	ds_write_b128 v1, v[10:13] offset:32768
	ds_write_b128 v1, v[30:33] offset:40960
	v_pk_mul_f32 v[12:13], v[4:5], v[36:37]
	v_pk_mul_f32 v[10:11], v[2:3], v[34:35]
	ds_write_b128 v1, v[10:13] offset:49152
	v_pk_add_f32 v[10:11], v[40:41], 1.0 op_sel_hi:[1,0]
	v_pk_add_f32 v[14:15], v[38:39], 1.0 op_sel_hi:[1,0]
	v_pk_mul_f32 v[12:13], v[8:9], v[10:11]
	v_pk_mul_f32 v[10:11], v[6:7], v[14:15]
	ds_write_b128 v1, v[10:13] offset:57344
	v_add_u32_e32 v10, 0x10000, v1
	v_add_u32_e32 v14, 0x12000, v1
	ds_write_b128 v10, v[42:45]
	v_pk_mul_f32 v[12:13], v[4:5], v[48:49]
	v_pk_mul_f32 v[10:11], v[2:3], v[46:47]
	ds_write_b128 v14, v[10:13]
	v_pk_add_f32 v[10:11], v[52:53], 1.0 op_sel_hi:[1,0]
	v_pk_add_f32 v[14:15], v[50:51], 1.0 op_sel_hi:[1,0]
	v_pk_mul_f32 v[12:13], v[8:9], v[10:11]
	v_pk_mul_f32 v[10:11], v[6:7], v[14:15]
	v_add_u32_e32 v14, 0x14000, v1
	ds_write_b128 v14, v[10:13]
	v_add_u32_e32 v10, 0x16000, v1
	ds_write_b128 v10, v[54:57]
	v_pk_mul_f32 v[4:5], v[4:5], v[60:61]
	v_pk_mul_f32 v[2:3], v[2:3], v[58:59]
	v_add_u32_e32 v10, 0x18000, v1
	ds_write_b128 v10, v[2:5]
	v_pk_add_f32 v[2:3], v[64:65], 1.0 op_sel_hi:[1,0]
	v_pk_add_f32 v[10:11], v[62:63], 1.0 op_sel_hi:[1,0]
	v_pk_mul_f32 v[4:5], v[8:9], v[2:3]
	v_pk_mul_f32 v[2:3], v[6:7], v[10:11]
	v_add_u32_e32 v6, 0x1a000, v1
	v_add_u32_e32 v1, 0x1c000, v1
	ds_write_b128 v6, v[2:5]
	ds_write_b128 v1, v[66:69]
	s_waitcnt lgkmcnt(0)
	s_barrier
	s_cbranch_scc1 .LBB0_1573
	v_mbcnt_lo_u32_b32 v1, -1, 0
	v_mbcnt_hi_u32_b32 v3, -1, v1
	v_and_b32_e32 v1, 64, v3
	v_add_u32_e32 v5, 64, v1
	v_xor_b32_e32 v1, 1, v3
	v_cmp_lt_i32_e32 vcc, v1, v5
	v_xor_b32_e32 v7, 2, v3
	v_lshlrev_b32_e32 v10, 3, v178
	v_cndmask_b32_e32 v1, v3, v1, vcc
	v_cmp_lt_i32_e32 vcc, v7, v5
	v_mov_b32_e32 v11, v181
	v_lshl_add_u64 v[12:13], s[88:89], 0, v[10:11]
	v_cndmask_b32_e32 v7, v3, v7, vcc
	v_lshlrev_b32_e32 v62, 2, v7
	v_xor_b32_e32 v7, 4, v3
	v_cmp_lt_i32_e32 vcc, v7, v5
	s_mov_b64 s[2:3], 0x17d00000
	v_or_b32_e32 v2, 0x100, v178
	v_cndmask_b32_e32 v7, v3, v7, vcc
	v_lshlrev_b32_e32 v63, 2, v7
	v_xor_b32_e32 v7, 8, v3
	v_cmp_lt_i32_e32 vcc, v7, v5
	v_or_b32_e32 v4, 0x140, v178
	v_or_b32_e32 v6, 0x180, v178
	v_cndmask_b32_e32 v7, v3, v7, vcc
	v_lshlrev_b32_e32 v64, 2, v7
	v_xor_b32_e32 v7, 16, v3
	v_cmp_lt_i32_e32 vcc, v7, v5
	v_or_b32_e32 v8, 0x1c0, v178
	v_lshl_add_u64 v[34:35], v[12:13], 0, s[2:3]
	v_cndmask_b32_e32 v7, v3, v7, vcc
	v_lshlrev_b32_e32 v65, 2, v7
	v_xor_b32_e32 v7, 32, v3
	v_cmp_lt_i32_e32 vcc, v7, v5
	v_lshlrev_b32_e32 v12, 4, v178
	v_mov_b32_e32 v13, v181
	v_cndmask_b32_e32 v3, v3, v7, vcc
	s_lshl_b32 s12, s61, 3
	v_lshlrev_b32_e32 v1, 2, v1
	v_lshlrev_b32_e32 v66, 2, v3
	v_lshl_add_u64 v[36:37], s[90:91], 0, v[10:11]
	v_add_u32_e32 v67, 0, v12
	v_lshl_add_u64 v[38:39], s[94:95], 0, v[10:11]
	v_lshl_add_u64 v[40:41], s[88:89], 0, v[12:13]
	v_lshlrev_b32_e32 v68, 4, v178
	v_lshlrev_b32_e32 v69, 4, v2
	v_lshlrev_b32_e32 v70, 4, v4
	v_lshlrev_b32_e32 v71, 4, v6
	v_lshlrev_b32_e32 v72, 4, v8
	s_mov_b32 s13, 0x4b900000
	s_mov_b32 s14, 0x4b901000
	v_mov_b32_e32 v73, 0x358637bd
	s_branch .LBB0_1568

.LBB0_1830:
	s_cmp_lt_i32 s84, 18
	s_cselect_b64 s[0:1], -1, 0
	s_cmp_gt_i32 s85, 17
	s_cselect_b64 s[2:3], -1, 0
	s_and_b64 s[0:1], s[0:1], s[2:3]
	s_andn2_b64 vcc, exec, s[0:1]
	s_cbranch_vccnz .LBB0_1893
	v_mov_b32_e32 v181, 0
	v_lshl_add_u64 v[2:3], s[48:49], 0, v[180:181]
	v_add_co_u32_e32 v4, vcc, 0xe000, v2
	v_lshl_add_u64 v[66:67], s[88:89], 0, v[180:181]
	s_nop 0
	v_addc_co_u32_e32 v5, vcc, 0, v3, vcc
	v_add_co_u32_e32 v6, vcc, 0x10000, v2
	s_mov_b32 s0, 0x976000
	s_nop 0
	v_addc_co_u32_e32 v7, vcc, 0, v3, vcc
	v_add_co_u32_e32 v10, vcc, 0x946000, v66
	global_load_dwordx4 v[2:5], v[4:5], off nt
	s_nop 0
	global_load_dwordx4 v[6:9], v[6:7], off nt
	v_addc_co_u32_e32 v11, vcc, 0, v67, vcc
	v_add_co_u32_e32 v14, vcc, 0x97a000, v66
	v_add_u32_e32 v1, 0, v180
	s_nop 0
	v_addc_co_u32_e32 v15, vcc, 0, v67, vcc
	v_add_co_u32_e32 v18, vcc, 0x978000, v66
	global_load_dwordx4 v[10:13], v[10:11], off nt
	s_nop 0
	global_load_dwordx4 v[14:17], v[14:15], off nt
	v_addc_co_u32_e32 v19, vcc, 0, v67, vcc
	v_add_co_u32_e32 v22, vcc, 0x952000, v66
	v_readlane_b32 s1, v250, 21
	s_nop 0
	v_addc_co_u32_e32 v23, vcc, 0, v67, vcc
	v_add_co_u32_e32 v26, vcc, 0x986000, v66
	global_load_dwordx4 v[18:21], v[18:19], off nt
	s_nop 0
	global_load_dwordx4 v[22:25], v[22:23], off nt
	v_addc_co_u32_e32 v27, vcc, 0, v67, vcc
	v_add_co_u32_e32 v30, vcc, 0x984000, v66
	s_waitcnt vmcnt(0)
	v_pk_mul_f32 v[12:13], v[4:5], v[12:13]
	v_addc_co_u32_e32 v31, vcc, 0, v67, vcc
	v_add_co_u32_e32 v34, vcc, 0x95e000, v66
	global_load_dwordx4 v[26:29], v[26:27], off nt
	s_nop 0
	global_load_dwordx4 v[30:33], v[30:31], off nt
	v_addc_co_u32_e32 v35, vcc, 0, v67, vcc
	v_add_co_u32_e32 v38, vcc, 0x992000, v66
	v_pk_mul_f32 v[10:11], v[2:3], v[10:11]
	s_nop 0
	v_addc_co_u32_e32 v39, vcc, 0, v67, vcc
	v_add_co_u32_e32 v42, vcc, 0x990000, v66
	global_load_dwordx4 v[34:37], v[34:35], off nt
	s_nop 0
	global_load_dwordx4 v[38:41], v[38:39], off nt
	v_addc_co_u32_e32 v43, vcc, 0, v67, vcc
	v_add_co_u32_e32 v46, vcc, 0x96a000, v66
	v_pk_add_f32 v[14:15], v[14:15], 1.0 op_sel_hi:[1,0]
	s_nop 0
	v_addc_co_u32_e32 v47, vcc, 0, v67, vcc
	v_add_co_u32_e32 v50, vcc, 0x99e000, v66
	global_load_dwordx4 v[42:45], v[42:43], off nt
	s_nop 0
	global_load_dwordx4 v[46:49], v[46:47], off nt
	v_addc_co_u32_e32 v51, vcc, 0, v67, vcc
	v_add_co_u32_e32 v54, vcc, 0x99c000, v66
	s_nop 1
	v_addc_co_u32_e32 v55, vcc, 0, v67, vcc
	v_add_co_u32_e32 v58, vcc, s0, v66
	global_load_dwordx4 v[50:53], v[50:51], off nt
	s_nop 0
	global_load_dwordx4 v[54:57], v[54:55], off nt
	v_addc_co_u32_e32 v59, vcc, 0, v67, vcc
	s_mov_b32 s0, 0x9aa000
	v_add_co_u32_e32 v62, vcc, s0, v66
	global_load_dwordx4 v[58:61], v[58:59], off nt
	s_nop 0
	v_addc_co_u32_e32 v63, vcc, 0, v67, vcc
	s_mov_b32 s0, 0x9a8000
	global_load_dwordx4 v[62:65], v[62:63], off nt
	v_add_co_u32_e32 v66, vcc, s0, v66
	ds_write_b128 v1, v[10:13]
	s_nop 0
	v_addc_co_u32_e32 v67, vcc, 0, v67, vcc
	global_load_dwordx4 v[66:69], v[66:67], off nt
	v_pk_add_f32 v[10:11], v[16:17], 1.0 op_sel_hi:[1,0]
	v_readlane_b32 s0, v250, 44
	v_pk_mul_f32 v[12:13], v[8:9], v[10:11]
	v_pk_mul_f32 v[10:11], v[6:7], v[14:15]
	ds_write_b128 v1, v[10:13] offset:8192
	ds_write_b128 v1, v[18:21] offset:16384
	v_pk_mul_f32 v[12:13], v[4:5], v[24:25]
	v_pk_mul_f32 v[10:11], v[2:3], v[22:23]
	ds_write_b128 v1, v[10:13] offset:24576
	s_lshl_b32 s0, s0, 3
	s_add_i32 s0, s0, s1
	s_cmpk_gt_i32 s0, 0x43ff
	s_waitcnt vmcnt(0)
	v_pk_add_f32 v[10:11], v[28:29], 1.0 op_sel_hi:[1,0]
	v_pk_add_f32 v[14:15], v[26:27], 1.0 op_sel_hi:[1,0]
	v_pk_mul_f32 v[12:13], v[8:9], v[10:11]
	v_pk_mul_f32 v[10:11], v[6:7], v[14:15]
	ds_write_b128 v1, v[10:13] offset:32768
	ds_write_b128 v1, v[30:33] offset:40960
	v_pk_mul_f32 v[12:13], v[4:5], v[36:37]
	v_pk_mul_f32 v[10:11], v[2:3], v[34:35]
	ds_write_b128 v1, v[10:13] offset:49152
	v_pk_add_f32 v[10:11], v[40:41], 1.0 op_sel_hi:[1,0]
	v_pk_add_f32 v[14:15], v[38:39], 1.0 op_sel_hi:[1,0]
	v_pk_mul_f32 v[12:13], v[8:9], v[10:11]
	v_pk_mul_f32 v[10:11], v[6:7], v[14:15]
	ds_write_b128 v1, v[10:13] offset:57344
	v_add_u32_e32 v10, 0x10000, v1
	v_add_u32_e32 v14, 0x12000, v1
	ds_write_b128 v10, v[42:45]
	v_pk_mul_f32 v[12:13], v[4:5], v[48:49]
	v_pk_mul_f32 v[10:11], v[2:3], v[46:47]
	ds_write_b128 v14, v[10:13]
	v_pk_add_f32 v[10:11], v[52:53], 1.0 op_sel_hi:[1,0]
	v_pk_add_f32 v[14:15], v[50:51], 1.0 op_sel_hi:[1,0]
	v_pk_mul_f32 v[12:13], v[8:9], v[10:11]
	v_pk_mul_f32 v[10:11], v[6:7], v[14:15]
	v_add_u32_e32 v14, 0x14000, v1
	ds_write_b128 v14, v[10:13]
	v_add_u32_e32 v10, 0x16000, v1
	ds_write_b128 v10, v[54:57]
	v_pk_mul_f32 v[4:5], v[4:5], v[60:61]
	v_pk_mul_f32 v[2:3], v[2:3], v[58:59]
	v_add_u32_e32 v10, 0x18000, v1
	ds_write_b128 v10, v[2:5]
	v_pk_add_f32 v[2:3], v[64:65], 1.0 op_sel_hi:[1,0]
	v_pk_add_f32 v[10:11], v[62:63], 1.0 op_sel_hi:[1,0]
	v_pk_mul_f32 v[4:5], v[8:9], v[2:3]
	v_pk_mul_f32 v[2:3], v[6:7], v[10:11]
	v_add_u32_e32 v6, 0x1a000, v1
	v_add_u32_e32 v1, 0x1c000, v1
	ds_write_b128 v6, v[2:5]
	ds_write_b128 v1, v[66:69]
	s_waitcnt lgkmcnt(0)
	s_barrier
	s_cbranch_scc1 .LBB0_1839
	v_mbcnt_lo_u32_b32 v1, -1, 0
	v_mbcnt_hi_u32_b32 v3, -1, v1
	v_and_b32_e32 v1, 64, v3
	v_add_u32_e32 v5, 64, v1
	v_xor_b32_e32 v1, 1, v3
	v_cmp_lt_i32_e32 vcc, v1, v5
	v_xor_b32_e32 v7, 2, v3
	v_lshlrev_b32_e32 v10, 3, v178
	v_cndmask_b32_e32 v1, v3, v1, vcc
	v_cmp_lt_i32_e32 vcc, v7, v5
	v_mov_b32_e32 v11, v181
	v_lshl_add_u64 v[12:13], s[88:89], 0, v[10:11]
	v_cndmask_b32_e32 v7, v3, v7, vcc
	v_lshlrev_b32_e32 v62, 2, v7
	v_xor_b32_e32 v7, 4, v3
	v_cmp_lt_i32_e32 vcc, v7, v5
	s_mov_b64 s[2:3], 0x17d00000
	v_or_b32_e32 v2, 0x100, v178
	v_cndmask_b32_e32 v7, v3, v7, vcc
	v_lshlrev_b32_e32 v63, 2, v7
	v_xor_b32_e32 v7, 8, v3
	v_cmp_lt_i32_e32 vcc, v7, v5
	v_or_b32_e32 v4, 0x140, v178
	v_or_b32_e32 v6, 0x180, v178
	v_cndmask_b32_e32 v7, v3, v7, vcc
	v_lshlrev_b32_e32 v64, 2, v7
	v_xor_b32_e32 v7, 16, v3
	v_cmp_lt_i32_e32 vcc, v7, v5
	v_or_b32_e32 v8, 0x1c0, v178
	v_lshl_add_u64 v[34:35], v[12:13], 0, s[2:3]
	v_cndmask_b32_e32 v7, v3, v7, vcc
	v_lshlrev_b32_e32 v65, 2, v7
	v_xor_b32_e32 v7, 32, v3
	v_cmp_lt_i32_e32 vcc, v7, v5
	v_lshlrev_b32_e32 v12, 4, v178
	v_mov_b32_e32 v13, v181
	v_cndmask_b32_e32 v3, v3, v7, vcc
	s_lshl_b32 s12, s61, 3
	v_lshlrev_b32_e32 v1, 2, v1
	v_lshlrev_b32_e32 v66, 2, v3
	v_lshl_add_u64 v[36:37], s[90:91], 0, v[10:11]
	v_add_u32_e32 v67, 0, v12
	v_lshl_add_u64 v[38:39], s[94:95], 0, v[10:11]
	v_lshl_add_u64 v[40:41], s[88:89], 0, v[12:13]
	v_lshlrev_b32_e32 v68, 4, v178
	v_lshlrev_b32_e32 v69, 4, v2
	v_lshlrev_b32_e32 v70, 4, v4
	v_lshlrev_b32_e32 v71, 4, v6
	v_lshlrev_b32_e32 v72, 4, v8
	s_mov_b32 s13, 0x4b900000
	s_mov_b32 s14, 0x4b901000
	v_mov_b32_e32 v73, 0x358637bd
	s_branch .LBB0_1834

.LBB0_2394:
	s_cmp_lt_i32 s84, 23
	s_cselect_b64 s[0:1], -1, 0
	s_cmp_gt_i32 s85, 22
	s_cselect_b64 s[2:3], -1, 0
	s_and_b64 s[0:1], s[0:1], s[2:3]
	s_andn2_b64 vcc, exec, s[0:1]
	s_cbranch_vccnz .LBB0_2457
	v_mov_b32_e32 v181, 0
	v_lshl_add_u64 v[2:3], s[48:49], 0, v[180:181]
	v_add_co_u32_e32 v10, vcc, 0x12000, v2
	v_lshl_add_u64 v[66:67], s[88:89], 0, v[180:181]
	s_nop 0
	v_addc_co_u32_e32 v11, vcc, 0, v3, vcc
	v_add_co_u32_e32 v12, vcc, 0x14000, v2
	s_mov_b32 s0, 0x9ac000
	s_nop 0
	v_addc_co_u32_e32 v13, vcc, 0, v3, vcc
	s_waitcnt lgkmcnt(0)
	global_load_dwordx4 v[6:9], v[10:11], off nt
	global_load_dwordx4 v[2:5], v[12:13], off nt
	v_add_co_u32_e32 v10, vcc, 0x97c000, v66
	v_add_u32_e32 v1, 0, v180
	s_nop 0
	v_addc_co_u32_e32 v11, vcc, 0, v67, vcc
	v_add_co_u32_e32 v14, vcc, 0x980000, v66
	v_readlane_b32 s1, v250, 21
	s_nop 0
	v_addc_co_u32_e32 v15, vcc, 0, v67, vcc
	v_add_co_u32_e32 v18, vcc, 0x97e000, v66
	global_load_dwordx4 v[10:13], v[10:11], off nt
	s_nop 0
	global_load_dwordx4 v[14:17], v[14:15], off nt
	v_addc_co_u32_e32 v19, vcc, 0, v67, vcc
	v_add_co_u32_e32 v22, vcc, 0x988000, v66
	s_waitcnt vmcnt(0)
	v_pk_mul_f32 v[12:13], v[8:9], v[12:13]
	v_addc_co_u32_e32 v23, vcc, 0, v67, vcc
	v_add_co_u32_e32 v26, vcc, 0x98c000, v66
	global_load_dwordx4 v[18:21], v[18:19], off nt
	s_nop 0
	global_load_dwordx4 v[22:25], v[22:23], off nt
	v_addc_co_u32_e32 v27, vcc, 0, v67, vcc
	v_add_co_u32_e32 v30, vcc, 0x98a000, v66
	v_pk_mul_f32 v[10:11], v[6:7], v[10:11]
	s_nop 0
	v_addc_co_u32_e32 v31, vcc, 0, v67, vcc
	v_add_co_u32_e32 v34, vcc, 0x994000, v66
	global_load_dwordx4 v[26:29], v[26:27], off nt
	s_nop 0
	global_load_dwordx4 v[30:33], v[30:31], off nt
	v_addc_co_u32_e32 v35, vcc, 0, v67, vcc
	v_add_co_u32_e32 v38, vcc, 0x998000, v66
	v_pk_add_f32 v[14:15], v[14:15], 1.0 op_sel_hi:[1,0]
	s_nop 0
	v_addc_co_u32_e32 v39, vcc, 0, v67, vcc
	v_add_co_u32_e32 v42, vcc, 0x996000, v66
	global_load_dwordx4 v[34:37], v[34:35], off nt
	s_nop 0
	global_load_dwordx4 v[38:41], v[38:39], off nt
	v_addc_co_u32_e32 v43, vcc, 0, v67, vcc
	v_add_co_u32_e32 v46, vcc, 0x9a0000, v66
	s_nop 1
	v_addc_co_u32_e32 v47, vcc, 0, v67, vcc
	v_add_co_u32_e32 v50, vcc, 0x9a4000, v66
	global_load_dwordx4 v[42:45], v[42:43], off nt
	s_nop 0
	global_load_dwordx4 v[46:49], v[46:47], off nt
	v_addc_co_u32_e32 v51, vcc, 0, v67, vcc
	v_add_co_u32_e32 v54, vcc, 0x9a2000, v66
	s_nop 1
	v_addc_co_u32_e32 v55, vcc, 0, v67, vcc
	v_add_co_u32_e32 v58, vcc, s0, v66
	global_load_dwordx4 v[50:53], v[50:51], off nt
	s_nop 0
	global_load_dwordx4 v[54:57], v[54:55], off nt
	v_addc_co_u32_e32 v59, vcc, 0, v67, vcc
	s_mov_b32 s0, 0x9b0000
	v_add_co_u32_e32 v62, vcc, s0, v66
	global_load_dwordx4 v[58:61], v[58:59], off nt
	s_nop 0
	v_addc_co_u32_e32 v63, vcc, 0, v67, vcc
	s_mov_b32 s0, 0x9ae000
	global_load_dwordx4 v[62:65], v[62:63], off nt
	v_add_co_u32_e32 v66, vcc, s0, v66
	ds_write_b128 v1, v[10:13]
	s_nop 0
	v_addc_co_u32_e32 v67, vcc, 0, v67, vcc
	global_load_dwordx4 v[66:69], v[66:67], off nt
	v_pk_add_f32 v[10:11], v[16:17], 1.0 op_sel_hi:[1,0]
	v_readlane_b32 s0, v250, 44
	v_pk_mul_f32 v[12:13], v[4:5], v[10:11]
	v_pk_mul_f32 v[10:11], v[2:3], v[14:15]
	ds_write_b128 v1, v[10:13] offset:8192
	s_waitcnt vmcnt(12)
	ds_write_b128 v1, v[18:21] offset:16384
	s_waitcnt vmcnt(11)
	v_pk_mul_f32 v[12:13], v[8:9], v[24:25]
	v_pk_mul_f32 v[10:11], v[6:7], v[22:23]
	ds_write_b128 v1, v[10:13] offset:24576
	s_lshl_b32 s0, s0, 3
	s_add_i32 s0, s0, s1
	s_cmpk_gt_i32 s0, 0x43ff
	s_waitcnt vmcnt(10)
	v_pk_add_f32 v[10:11], v[28:29], 1.0 op_sel_hi:[1,0]
	v_pk_add_f32 v[14:15], v[26:27], 1.0 op_sel_hi:[1,0]
	v_pk_mul_f32 v[12:13], v[4:5], v[10:11]
	v_pk_mul_f32 v[10:11], v[2:3], v[14:15]
	ds_write_b128 v1, v[10:13] offset:32768
	s_waitcnt vmcnt(9)
	ds_write_b128 v1, v[30:33] offset:40960
	s_waitcnt vmcnt(8)
	v_pk_mul_f32 v[12:13], v[8:9], v[36:37]
	v_pk_mul_f32 v[10:11], v[6:7], v[34:35]
	ds_write_b128 v1, v[10:13] offset:49152
	s_waitcnt vmcnt(7)
	v_pk_add_f32 v[10:11], v[40:41], 1.0 op_sel_hi:[1,0]
	v_pk_add_f32 v[14:15], v[38:39], 1.0 op_sel_hi:[1,0]
	v_pk_mul_f32 v[12:13], v[4:5], v[10:11]
	v_pk_mul_f32 v[10:11], v[2:3], v[14:15]
	ds_write_b128 v1, v[10:13] offset:57344
	v_add_u32_e32 v10, 0x10000, v1
	v_add_u32_e32 v14, 0x12000, v1
	s_waitcnt vmcnt(6)
	ds_write_b128 v10, v[42:45]
	s_waitcnt vmcnt(5)
	v_pk_mul_f32 v[12:13], v[8:9], v[48:49]
	v_pk_mul_f32 v[10:11], v[6:7], v[46:47]
	ds_write_b128 v14, v[10:13]
	s_waitcnt vmcnt(4)
	v_pk_add_f32 v[10:11], v[52:53], 1.0 op_sel_hi:[1,0]
	v_pk_add_f32 v[14:15], v[50:51], 1.0 op_sel_hi:[1,0]
	v_pk_mul_f32 v[12:13], v[4:5], v[10:11]
	v_pk_mul_f32 v[10:11], v[2:3], v[14:15]
	v_add_u32_e32 v14, 0x14000, v1
	ds_write_b128 v14, v[10:13]
	v_add_u32_e32 v10, 0x16000, v1
	s_waitcnt vmcnt(3)
	ds_write_b128 v10, v[54:57]
	s_waitcnt vmcnt(2)
	v_pk_mul_f32 v[8:9], v[8:9], v[60:61]
	v_pk_mul_f32 v[6:7], v[6:7], v[58:59]
	v_add_u32_e32 v10, 0x18000, v1
	ds_write_b128 v10, v[6:9]
	s_waitcnt vmcnt(1)
	v_pk_add_f32 v[6:7], v[64:65], 1.0 op_sel_hi:[1,0]
	v_pk_add_f32 v[8:9], v[62:63], 1.0 op_sel_hi:[1,0]
	v_pk_mul_f32 v[4:5], v[4:5], v[6:7]
	v_pk_mul_f32 v[2:3], v[2:3], v[8:9]
	v_add_u32_e32 v6, 0x1a000, v1
	v_add_u32_e32 v1, 0x1c000, v1
	ds_write_b128 v6, v[2:5]
	s_waitcnt vmcnt(0)
	ds_write_b128 v1, v[66:69]
	s_waitcnt lgkmcnt(0)
	s_barrier
	s_cbranch_scc1 .LBB0_2403
	v_mbcnt_lo_u32_b32 v1, -1, 0
	v_mbcnt_hi_u32_b32 v3, -1, v1
	v_and_b32_e32 v1, 64, v3
	v_add_u32_e32 v5, 64, v1
	v_xor_b32_e32 v1, 1, v3
	v_cmp_lt_i32_e32 vcc, v1, v5
	v_xor_b32_e32 v7, 2, v3
	v_lshlrev_b32_e32 v10, 3, v178
	v_cndmask_b32_e32 v1, v3, v1, vcc
	v_cmp_lt_i32_e32 vcc, v7, v5
	v_mov_b32_e32 v11, v181
	v_lshl_add_u64 v[12:13], s[88:89], 0, v[10:11]
	v_cndmask_b32_e32 v7, v3, v7, vcc
	v_lshlrev_b32_e32 v62, 2, v7
	v_xor_b32_e32 v7, 4, v3
	v_cmp_lt_i32_e32 vcc, v7, v5
	s_mov_b64 s[2:3], 0x17d00000
	v_or_b32_e32 v2, 0x100, v178
	v_cndmask_b32_e32 v7, v3, v7, vcc
	v_lshlrev_b32_e32 v63, 2, v7
	v_xor_b32_e32 v7, 8, v3
	v_cmp_lt_i32_e32 vcc, v7, v5
	v_or_b32_e32 v4, 0x140, v178
	v_or_b32_e32 v6, 0x180, v178
	v_cndmask_b32_e32 v7, v3, v7, vcc
	v_lshlrev_b32_e32 v64, 2, v7
	v_xor_b32_e32 v7, 16, v3
	v_cmp_lt_i32_e32 vcc, v7, v5
	v_or_b32_e32 v8, 0x1c0, v178
	v_lshl_add_u64 v[34:35], v[12:13], 0, s[2:3]
	v_cndmask_b32_e32 v7, v3, v7, vcc
	v_lshlrev_b32_e32 v65, 2, v7
	v_xor_b32_e32 v7, 32, v3
	v_cmp_lt_i32_e32 vcc, v7, v5
	v_lshlrev_b32_e32 v12, 4, v178
	v_mov_b32_e32 v13, v181
	v_cndmask_b32_e32 v3, v3, v7, vcc
	s_lshl_b32 s12, s61, 3
	v_lshlrev_b32_e32 v1, 2, v1
	v_lshlrev_b32_e32 v66, 2, v3
	v_lshl_add_u64 v[36:37], s[90:91], 0, v[10:11]
	v_add_u32_e32 v67, 0, v12
	v_lshl_add_u64 v[38:39], s[94:95], 0, v[10:11]
	v_lshl_add_u64 v[40:41], s[88:89], 0, v[12:13]
	v_lshlrev_b32_e32 v68, 4, v178
	v_lshlrev_b32_e32 v69, 4, v2
	v_lshlrev_b32_e32 v70, 4, v4
	v_lshlrev_b32_e32 v71, 4, v6
	v_lshlrev_b32_e32 v72, 4, v8
	s_mov_b32 s13, 0x4b900000
	s_mov_b32 s14, 0x4b901000
	v_mov_b32_e32 v73, 0x358637bd
	s_branch .LBB0_2398

.LBB0_2656:
	s_cmp_lt_i32 s84, 26
	s_cselect_b64 s[0:1], -1, 0
	s_cmp_gt_i32 s85, 25
	s_cselect_b64 s[2:3], -1, 0
	s_and_b64 s[0:1], s[0:1], s[2:3]
	s_andn2_b64 vcc, exec, s[0:1]
	s_cbranch_vccnz .LBB0_2719
	v_mov_b32_e32 v181, 0
	v_lshl_add_u64 v[2:3], s[48:49], 0, v[180:181]
	v_add_co_u32_e32 v10, vcc, 0x16000, v2
	v_lshl_add_u64 v[66:67], s[88:89], 0, v[180:181]
	s_nop 0
	v_addc_co_u32_e32 v11, vcc, 0, v3, vcc
	v_add_co_u32_e32 v12, vcc, 0x18000, v2
	s_mov_b32 s0, 0x9b2000
	s_nop 0
	v_addc_co_u32_e32 v13, vcc, 0, v3, vcc
	v_add_co_u32_e32 v18, vcc, 0x982000, v66
	s_waitcnt lgkmcnt(0)
	global_load_dwordx4 v[6:9], v[10:11], off nt
	global_load_dwordx4 v[2:5], v[12:13], off nt
	v_addc_co_u32_e32 v19, vcc, 0, v67, vcc
	v_add_co_u32_e32 v20, vcc, 0x9b6000, v66
	v_add_u32_e32 v1, 0, v180
	s_nop 0
	v_addc_co_u32_e32 v21, vcc, 0, v67, vcc
	v_add_co_u32_e32 v26, vcc, 0x9b4000, v66
	global_load_dwordx4 v[10:13], v[18:19], off nt
	global_load_dwordx4 v[14:17], v[20:21], off nt
	v_addc_co_u32_e32 v27, vcc, 0, v67, vcc
	v_add_co_u32_e32 v28, vcc, 0x98e000, v66
	v_readlane_b32 s1, v250, 21
	s_nop 0
	v_addc_co_u32_e32 v29, vcc, 0, v67, vcc
	v_add_co_u32_e32 v34, vcc, 0x9c2000, v66
	global_load_dwordx4 v[18:21], v[26:27], off nt
	global_load_dwordx4 v[22:25], v[28:29], off nt
	v_addc_co_u32_e32 v35, vcc, 0, v67, vcc
	v_add_co_u32_e32 v36, vcc, 0x9c0000, v66
	s_waitcnt vmcnt(0)
	v_pk_mul_f32 v[12:13], v[8:9], v[12:13]
	v_addc_co_u32_e32 v37, vcc, 0, v67, vcc
	v_add_co_u32_e32 v42, vcc, 0x99a000, v66
	global_load_dwordx4 v[26:29], v[34:35], off nt
	global_load_dwordx4 v[30:33], v[36:37], off nt
	v_addc_co_u32_e32 v43, vcc, 0, v67, vcc
	v_add_co_u32_e32 v44, vcc, 0x9ce000, v66
	v_pk_mul_f32 v[10:11], v[6:7], v[10:11]
	s_nop 0
	v_addc_co_u32_e32 v45, vcc, 0, v67, vcc
	v_add_co_u32_e32 v50, vcc, 0x9cc000, v66
	global_load_dwordx4 v[34:37], v[42:43], off nt
	global_load_dwordx4 v[38:41], v[44:45], off nt
	v_addc_co_u32_e32 v51, vcc, 0, v67, vcc
	v_add_co_u32_e32 v52, vcc, 0x9a6000, v66
	v_pk_add_f32 v[14:15], v[14:15], 1.0 op_sel_hi:[1,0]
	s_nop 0
	v_addc_co_u32_e32 v53, vcc, 0, v67, vcc
	v_add_co_u32_e32 v58, vcc, 0x9da000, v66
	global_load_dwordx4 v[42:45], v[50:51], off nt
	global_load_dwordx4 v[46:49], v[52:53], off nt
	v_addc_co_u32_e32 v59, vcc, 0, v67, vcc
	v_add_co_u32_e32 v60, vcc, 0x9d8000, v66
	s_nop 1
	v_addc_co_u32_e32 v61, vcc, 0, v67, vcc
	global_load_dwordx4 v[50:53], v[58:59], off nt
	global_load_dwordx4 v[54:57], v[60:61], off nt
	v_add_co_u32_e32 v58, vcc, s0, v66
	s_mov_b32 s0, 0x9e6000
	s_nop 0
	v_addc_co_u32_e32 v59, vcc, 0, v67, vcc
	v_add_co_u32_e32 v62, vcc, s0, v66
	global_load_dwordx4 v[58:61], v[58:59], off nt
	s_nop 0
	v_addc_co_u32_e32 v63, vcc, 0, v67, vcc
	s_mov_b32 s0, 0x9e4000
	global_load_dwordx4 v[62:65], v[62:63], off nt
	v_add_co_u32_e32 v66, vcc, s0, v66
	ds_write_b128 v1, v[10:13]
	s_nop 0
	v_addc_co_u32_e32 v67, vcc, 0, v67, vcc
	global_load_dwordx4 v[66:69], v[66:67], off nt
	v_pk_add_f32 v[10:11], v[16:17], 1.0 op_sel_hi:[1,0]
	v_readlane_b32 s0, v250, 44
	v_pk_mul_f32 v[12:13], v[4:5], v[10:11]
	v_pk_mul_f32 v[10:11], v[2:3], v[14:15]
	ds_write_b128 v1, v[10:13] offset:8192
	ds_write_b128 v1, v[18:21] offset:16384
	v_pk_mul_f32 v[12:13], v[8:9], v[24:25]
	v_pk_mul_f32 v[10:11], v[6:7], v[22:23]
	ds_write_b128 v1, v[10:13] offset:24576
	s_lshl_b32 s0, s0, 3
	s_add_i32 s0, s0, s1
	s_cmpk_gt_i32 s0, 0x43ff
	s_waitcnt vmcnt(10)
	v_pk_add_f32 v[10:11], v[28:29], 1.0 op_sel_hi:[1,0]
	v_pk_add_f32 v[14:15], v[26:27], 1.0 op_sel_hi:[1,0]
	v_pk_mul_f32 v[12:13], v[4:5], v[10:11]
	v_pk_mul_f32 v[10:11], v[2:3], v[14:15]
	ds_write_b128 v1, v[10:13] offset:32768
	s_waitcnt vmcnt(9)
	ds_write_b128 v1, v[30:33] offset:40960
	s_waitcnt vmcnt(8)
	v_pk_mul_f32 v[12:13], v[8:9], v[36:37]
	v_pk_mul_f32 v[10:11], v[6:7], v[34:35]
	ds_write_b128 v1, v[10:13] offset:49152
	s_waitcnt vmcnt(7)
	v_pk_add_f32 v[10:11], v[40:41], 1.0 op_sel_hi:[1,0]
	v_pk_add_f32 v[14:15], v[38:39], 1.0 op_sel_hi:[1,0]
	v_pk_mul_f32 v[12:13], v[4:5], v[10:11]
	v_pk_mul_f32 v[10:11], v[2:3], v[14:15]
	ds_write_b128 v1, v[10:13] offset:57344
	v_add_u32_e32 v10, 0x10000, v1
	v_add_u32_e32 v14, 0x12000, v1
	s_waitcnt vmcnt(6)
	ds_write_b128 v10, v[42:45]
	s_waitcnt vmcnt(5)
	v_pk_mul_f32 v[12:13], v[8:9], v[48:49]
	v_pk_mul_f32 v[10:11], v[6:7], v[46:47]
	ds_write_b128 v14, v[10:13]
	s_waitcnt vmcnt(4)
	v_pk_add_f32 v[10:11], v[52:53], 1.0 op_sel_hi:[1,0]
	v_pk_add_f32 v[14:15], v[50:51], 1.0 op_sel_hi:[1,0]
	v_pk_mul_f32 v[12:13], v[4:5], v[10:11]
	v_pk_mul_f32 v[10:11], v[2:3], v[14:15]
	v_add_u32_e32 v14, 0x14000, v1
	ds_write_b128 v14, v[10:13]
	v_add_u32_e32 v10, 0x16000, v1
	s_waitcnt vmcnt(3)
	ds_write_b128 v10, v[54:57]
	v_add_u32_e32 v10, 0x18000, v1
	s_waitcnt vmcnt(2)
	v_pk_mul_f32 v[8:9], v[8:9], v[60:61]
	v_pk_mul_f32 v[6:7], v[6:7], v[58:59]
	ds_write_b128 v10, v[6:9]
	s_waitcnt vmcnt(1)
	v_pk_add_f32 v[6:7], v[64:65], 1.0 op_sel_hi:[1,0]
	v_pk_add_f32 v[8:9], v[62:63], 1.0 op_sel_hi:[1,0]
	v_pk_mul_f32 v[4:5], v[4:5], v[6:7]
	v_pk_mul_f32 v[2:3], v[2:3], v[8:9]
	v_add_u32_e32 v6, 0x1a000, v1
	v_add_u32_e32 v1, 0x1c000, v1
	ds_write_b128 v6, v[2:5]
	s_waitcnt vmcnt(0)
	ds_write_b128 v1, v[66:69]
	s_waitcnt lgkmcnt(0)
	s_barrier
	s_cbranch_scc1 .LBB0_2665
	v_mbcnt_lo_u32_b32 v1, -1, 0
	v_mbcnt_hi_u32_b32 v3, -1, v1
	v_and_b32_e32 v1, 64, v3
	v_add_u32_e32 v5, 64, v1
	v_xor_b32_e32 v1, 1, v3
	v_cmp_lt_i32_e32 vcc, v1, v5
	v_xor_b32_e32 v7, 2, v3
	v_lshlrev_b32_e32 v10, 3, v178
	v_cndmask_b32_e32 v1, v3, v1, vcc
	v_cmp_lt_i32_e32 vcc, v7, v5
	v_mov_b32_e32 v11, v181
	v_lshl_add_u64 v[12:13], s[88:89], 0, v[10:11]
	v_cndmask_b32_e32 v7, v3, v7, vcc
	v_lshlrev_b32_e32 v62, 2, v7
	v_xor_b32_e32 v7, 4, v3
	v_cmp_lt_i32_e32 vcc, v7, v5
	s_mov_b64 s[2:3], 0x17d00000
	v_or_b32_e32 v2, 0x100, v178
	v_cndmask_b32_e32 v7, v3, v7, vcc
	v_lshlrev_b32_e32 v63, 2, v7
	v_xor_b32_e32 v7, 8, v3
	v_cmp_lt_i32_e32 vcc, v7, v5
	v_or_b32_e32 v4, 0x140, v178
	v_or_b32_e32 v6, 0x180, v178
	v_cndmask_b32_e32 v7, v3, v7, vcc
	v_lshlrev_b32_e32 v64, 2, v7
	v_xor_b32_e32 v7, 16, v3
	v_cmp_lt_i32_e32 vcc, v7, v5
	v_or_b32_e32 v8, 0x1c0, v178
	v_lshl_add_u64 v[34:35], v[12:13], 0, s[2:3]
	v_cndmask_b32_e32 v7, v3, v7, vcc
	v_lshlrev_b32_e32 v65, 2, v7
	v_xor_b32_e32 v7, 32, v3
	v_cmp_lt_i32_e32 vcc, v7, v5
	v_lshlrev_b32_e32 v12, 4, v178
	v_mov_b32_e32 v13, v181
	v_cndmask_b32_e32 v3, v3, v7, vcc
	s_lshl_b32 s12, s61, 3
	v_lshlrev_b32_e32 v1, 2, v1
	v_lshlrev_b32_e32 v66, 2, v3
	v_lshl_add_u64 v[36:37], s[90:91], 0, v[10:11]
	v_add_u32_e32 v67, 0, v12
	v_lshl_add_u64 v[38:39], s[94:95], 0, v[10:11]
	v_lshl_add_u64 v[40:41], s[88:89], 0, v[12:13]
	v_lshlrev_b32_e32 v68, 4, v178
	v_lshlrev_b32_e32 v69, 4, v2
	v_lshlrev_b32_e32 v70, 4, v4
	v_lshlrev_b32_e32 v71, 4, v6
	v_lshlrev_b32_e32 v72, 4, v8
	s_mov_b32 s13, 0x4b900000
	s_mov_b32 s14, 0x4b901000
	v_mov_b32_e32 v73, 0x358637bd
	s_branch .LBB0_2660

.LBB0_2664:
	v_lshl_add_u64 v[74:75], v[60:61], 0, s[8:9]
	v_add_co_u32_e32 v106, vcc, s13, v74
	s_add_u32 s8, s8, 0x800000
	s_nop 0
	v_addc_co_u32_e32 v107, vcc, 0, v75, vcc
	v_add_co_u32_e32 v108, vcc, s14, v74
	s_addc_u32 s9, s9, 0
	s_nop 0
	v_addc_co_u32_e32 v109, vcc, 0, v75, vcc
	global_load_dwordx4 v[74:77], v[108:109], off offset:-4096 nt
	global_load_dwordx4 v[78:81], v[106:107], off offset:1024 nt
	global_load_dwordx4 v[82:85], v[106:107], off offset:2048 nt
	global_load_dwordx4 v[86:89], v[106:107], off offset:3072 nt
	global_load_dwordx4 v[90:93], v[108:109], off nt
	global_load_dwordx4 v[94:97], v[108:109], off offset:1024 nt
	global_load_dwordx4 v[98:101], v[108:109], off offset:2048 nt
	global_load_dwordx4 v[102:105], v[108:109], off offset:3072 nt
	s_cmp_lg_u32 s8, 0x1800000
	s_waitcnt vmcnt(7)
	v_pk_add_f32 v[32:33], v[32:33], v[76:77]
	v_pk_add_f32 v[30:31], v[30:31], v[74:75]
	s_waitcnt vmcnt(6)
	v_pk_add_f32 v[28:29], v[28:29], v[80:81]
	v_pk_add_f32 v[26:27], v[26:27], v[78:79]
	s_waitcnt vmcnt(5)
	v_pk_add_f32 v[24:25], v[24:25], v[84:85]
	v_pk_add_f32 v[22:23], v[22:23], v[82:83]
	s_waitcnt vmcnt(4)
	v_pk_add_f32 v[20:21], v[20:21], v[88:89]
	v_pk_add_f32 v[18:19], v[18:19], v[86:87]
	s_waitcnt vmcnt(3)
	v_pk_add_f32 v[16:17], v[16:17], v[92:93]
	v_pk_add_f32 v[14:15], v[14:15], v[90:91]
	s_waitcnt vmcnt(2)
	v_pk_add_f32 v[12:13], v[12:13], v[96:97]
	v_pk_add_f32 v[10:11], v[10:11], v[94:95]
	s_waitcnt vmcnt(1)
	v_pk_add_f32 v[8:9], v[8:9], v[100:101]
	v_pk_add_f32 v[6:7], v[6:7], v[98:99]
	s_waitcnt vmcnt(0)
	v_pk_add_f32 v[4:5], v[4:5], v[104:105]
	v_pk_add_f32 v[2:3], v[2:3], v[102:103]
	s_cbranch_scc1 .LBB0_2664
	s_branch .LBB0_2659

.LBB0_3121:
	s_cmp_lt_i32 s84, 30
	s_cselect_b64 s[0:1], -1, 0
	s_cmp_gt_i32 s85, 29
	s_cselect_b64 s[2:3], -1, 0
	s_and_b64 s[0:1], s[0:1], s[2:3]
	s_andn2_b64 vcc, exec, s[0:1]
	s_cbranch_vccnz .LBB0_3181
	v_mov_b32_e32 v181, 0
	v_lshl_add_u64 v[2:3], s[48:49], 0, v[180:181]
	v_add_co_u32_e32 v10, vcc, 0x1a000, v2
	v_lshl_add_u64 v[66:67], s[88:89], 0, v[180:181]
	s_nop 0
	v_addc_co_u32_e32 v11, vcc, 0, v3, vcc
	v_add_co_u32_e32 v12, vcc, 0x1c000, v2
	s_mov_b32 s0, 0x9e8000
	s_nop 0
	v_addc_co_u32_e32 v13, vcc, 0, v3, vcc
	v_add_co_u32_e32 v18, vcc, 0x9b8000, v66
	s_waitcnt lgkmcnt(0)
	global_load_dwordx4 v[6:9], v[10:11], off nt
	global_load_dwordx4 v[2:5], v[12:13], off nt
	v_addc_co_u32_e32 v19, vcc, 0, v67, vcc
	v_add_co_u32_e32 v20, vcc, 0x9bc000, v66
	v_add_u32_e32 v1, 0, v180
	s_nop 0
	v_addc_co_u32_e32 v21, vcc, 0, v67, vcc
	v_add_co_u32_e32 v26, vcc, 0x9ba000, v66
	global_load_dwordx4 v[10:13], v[18:19], off nt
	global_load_dwordx4 v[14:17], v[20:21], off nt
	v_addc_co_u32_e32 v27, vcc, 0, v67, vcc
	v_add_co_u32_e32 v28, vcc, 0x9c4000, v66
	v_readlane_b32 s1, v250, 21
	s_nop 0
	v_addc_co_u32_e32 v29, vcc, 0, v67, vcc
	v_add_co_u32_e32 v34, vcc, 0x9c8000, v66
	global_load_dwordx4 v[18:21], v[26:27], off nt
	global_load_dwordx4 v[22:25], v[28:29], off nt
	v_addc_co_u32_e32 v35, vcc, 0, v67, vcc
	v_add_co_u32_e32 v36, vcc, 0x9c6000, v66
	s_waitcnt vmcnt(0)
	v_pk_mul_f32 v[12:13], v[8:9], v[12:13]
	v_addc_co_u32_e32 v37, vcc, 0, v67, vcc
	v_add_co_u32_e32 v42, vcc, 0x9d0000, v66
	global_load_dwordx4 v[26:29], v[34:35], off nt
	global_load_dwordx4 v[30:33], v[36:37], off nt
	v_addc_co_u32_e32 v43, vcc, 0, v67, vcc
	v_add_co_u32_e32 v44, vcc, 0x9d4000, v66
	v_pk_mul_f32 v[10:11], v[6:7], v[10:11]
	s_nop 0
	v_addc_co_u32_e32 v45, vcc, 0, v67, vcc
	v_add_co_u32_e32 v50, vcc, 0x9d2000, v66
	global_load_dwordx4 v[34:37], v[42:43], off nt
	global_load_dwordx4 v[38:41], v[44:45], off nt
	v_addc_co_u32_e32 v51, vcc, 0, v67, vcc
	v_add_co_u32_e32 v52, vcc, 0x9dc000, v66
	v_pk_add_f32 v[14:15], v[14:15], 1.0 op_sel_hi:[1,0]
	s_nop 0
	v_addc_co_u32_e32 v53, vcc, 0, v67, vcc
	v_add_co_u32_e32 v58, vcc, 0x9e0000, v66
	global_load_dwordx4 v[42:45], v[50:51], off nt
	global_load_dwordx4 v[46:49], v[52:53], off nt
	v_addc_co_u32_e32 v59, vcc, 0, v67, vcc
	v_add_co_u32_e32 v60, vcc, 0x9de000, v66
	s_nop 1
	v_addc_co_u32_e32 v61, vcc, 0, v67, vcc
	global_load_dwordx4 v[50:53], v[58:59], off nt
	global_load_dwordx4 v[54:57], v[60:61], off nt
	v_add_co_u32_e32 v58, vcc, s0, v66
	s_mov_b32 s0, 0x9ec000
	s_nop 0
	v_addc_co_u32_e32 v59, vcc, 0, v67, vcc
	v_add_co_u32_e32 v62, vcc, s0, v66
	global_load_dwordx4 v[58:61], v[58:59], off nt
	s_nop 0
	v_addc_co_u32_e32 v63, vcc, 0, v67, vcc
	s_mov_b32 s0, 0x9ea000
	global_load_dwordx4 v[62:65], v[62:63], off nt
	v_add_co_u32_e32 v66, vcc, s0, v66
	ds_write_b128 v1, v[10:13]
	s_nop 0
	v_addc_co_u32_e32 v67, vcc, 0, v67, vcc
	global_load_dwordx4 v[66:69], v[66:67], off nt
	v_pk_add_f32 v[10:11], v[16:17], 1.0 op_sel_hi:[1,0]
	v_readlane_b32 s0, v250, 44
	v_pk_mul_f32 v[12:13], v[4:5], v[10:11]
	v_pk_mul_f32 v[10:11], v[2:3], v[14:15]
	ds_write_b128 v1, v[10:13] offset:8192
	ds_write_b128 v1, v[18:21] offset:16384
	v_pk_mul_f32 v[12:13], v[8:9], v[24:25]
	v_pk_mul_f32 v[10:11], v[6:7], v[22:23]
	ds_write_b128 v1, v[10:13] offset:24576
	s_lshl_b32 s0, s0, 3
	s_add_i32 s0, s0, s1
	s_cmpk_gt_i32 s0, 0x43ff
	s_waitcnt vmcnt(10)
	v_pk_add_f32 v[10:11], v[28:29], 1.0 op_sel_hi:[1,0]
	v_pk_add_f32 v[14:15], v[26:27], 1.0 op_sel_hi:[1,0]
	v_pk_mul_f32 v[12:13], v[4:5], v[10:11]
	v_pk_mul_f32 v[10:11], v[2:3], v[14:15]
	ds_write_b128 v1, v[10:13] offset:32768
	s_waitcnt vmcnt(9)
	ds_write_b128 v1, v[30:33] offset:40960
	s_waitcnt vmcnt(8)
	v_pk_mul_f32 v[12:13], v[8:9], v[36:37]
	v_pk_mul_f32 v[10:11], v[6:7], v[34:35]
	ds_write_b128 v1, v[10:13] offset:49152
	s_waitcnt vmcnt(7)
	v_pk_add_f32 v[10:11], v[40:41], 1.0 op_sel_hi:[1,0]
	v_pk_add_f32 v[14:15], v[38:39], 1.0 op_sel_hi:[1,0]
	v_pk_mul_f32 v[12:13], v[4:5], v[10:11]
	v_pk_mul_f32 v[10:11], v[2:3], v[14:15]
	ds_write_b128 v1, v[10:13] offset:57344
	v_add_u32_e32 v10, 0x10000, v1
	v_add_u32_e32 v14, 0x12000, v1
	s_waitcnt vmcnt(6)
	ds_write_b128 v10, v[42:45]
	s_waitcnt vmcnt(5)
	v_pk_mul_f32 v[12:13], v[8:9], v[48:49]
	v_pk_mul_f32 v[10:11], v[6:7], v[46:47]
	ds_write_b128 v14, v[10:13]
	s_waitcnt vmcnt(4)
	v_pk_add_f32 v[10:11], v[52:53], 1.0 op_sel_hi:[1,0]
	v_pk_add_f32 v[14:15], v[50:51], 1.0 op_sel_hi:[1,0]
	v_pk_mul_f32 v[12:13], v[4:5], v[10:11]
	v_pk_mul_f32 v[10:11], v[2:3], v[14:15]
	v_add_u32_e32 v14, 0x14000, v1
	ds_write_b128 v14, v[10:13]
	v_add_u32_e32 v10, 0x16000, v1
	s_waitcnt vmcnt(3)
	ds_write_b128 v10, v[54:57]
	v_add_u32_e32 v10, 0x18000, v1
	s_waitcnt vmcnt(2)
	v_pk_mul_f32 v[8:9], v[8:9], v[60:61]
	v_pk_mul_f32 v[6:7], v[6:7], v[58:59]
	ds_write_b128 v10, v[6:9]
	s_waitcnt vmcnt(1)
	v_pk_add_f32 v[6:7], v[64:65], 1.0 op_sel_hi:[1,0]
	v_pk_add_f32 v[8:9], v[62:63], 1.0 op_sel_hi:[1,0]
	v_pk_mul_f32 v[4:5], v[4:5], v[6:7]
	v_pk_mul_f32 v[2:3], v[2:3], v[8:9]
	v_add_u32_e32 v6, 0x1a000, v1
	v_add_u32_e32 v1, 0x1c000, v1
	ds_write_b128 v6, v[2:5]
	s_waitcnt vmcnt(0)
	ds_write_b128 v1, v[66:69]
	s_waitcnt lgkmcnt(0)
	s_barrier
	s_cbranch_scc1 .LBB0_3127
	s_ashr_i32 s1, s0, 31
	s_lshl_b32 s2, s61, 3
	s_lshl_b64 s[4:5], s[0:1], 12
	s_add_u32 s4, s88, s4
	v_lshlrev_b32_e32 v2, 3, v178
	v_mov_b32_e32 v3, v181
	s_addc_u32 s5, s89, s5
	v_lshl_add_u64 v[2:3], s[4:5], 0, v[2:3]
	s_mov_b64 s[4:5], 0x24900e00
	s_ashr_i32 s3, s2, 31
	v_mbcnt_lo_u32_b32 v4, -1, 0
	v_lshl_add_u32 v1, v178, 4, 0
	v_lshl_add_u64 v[2:3], v[2:3], 0, s[4:5]
	s_lshl_b64 s[4:5], s[2:3], 12
	v_mov_b32_e32 v38, 0x358637bd
	s_mov_b32 s1, 0xfbc00000
	v_mbcnt_hi_u32_b32 v39, -1, v4
	s_branch .LBB0_3125

.LBB0_3125:
	s_mul_hi_i32 s3, s0, 0x78787879
	s_lshr_b32 s6, s3, 31
	s_ashr_i32 s3, s3, 11
	s_add_i32 s3, s3, s6
	s_mul_i32 s6, s3, 0xffffef00
	s_add_i32 s6, s0, s6
	s_cmpk_lt_i32 s6, 0x100
	s_cbranch_scc1 .LBB0_3124
	global_load_dwordx2 v[6:7], v[2:3], off offset:-3584 nt
	global_load_dwordx2 v[8:9], v[2:3], off offset:-3072 nt
	global_load_dwordx2 v[10:11], v[2:3], off offset:-2560 nt
	global_load_dwordx2 v[12:13], v[2:3], off offset:-2048 nt
	global_load_dwordx2 v[14:15], v[2:3], off offset:-1536 nt
	global_load_dwordx2 v[16:17], v[2:3], off offset:-1024 nt
	global_load_dwordx2 v[18:19], v[2:3], off offset:-512 nt
	global_load_dwordx2 v[20:21], v[2:3], off nt
	v_add_co_u32_e32 v4, vcc, 0xf3400000, v2
	s_mulk_i32 s3, 0x6000
	s_nop 0
	v_addc_co_u32_e32 v5, vcc, -1, v3, vcc
	global_load_dwordx2 v[22:23], v[4:5], off offset:-3584 nt
	global_load_dwordx2 v[24:25], v[4:5], off offset:-3072 nt
	global_load_dwordx2 v[26:27], v[4:5], off offset:-2560 nt
	global_load_dwordx2 v[28:29], v[4:5], off offset:-2048 nt
	global_load_dwordx2 v[30:31], v[4:5], off offset:-1536 nt
	global_load_dwordx2 v[32:33], v[4:5], off offset:-1024 nt
	global_load_dwordx2 v[34:35], v[4:5], off offset:-512 nt
	global_load_dwordx2 v[36:37], v[4:5], off nt
	v_add_u32_e32 v97, s3, v1
	s_waitcnt vmcnt(15)
	v_and_b32_e32 v41, 0xffff0000, v6
	v_and_b32_e32 v43, 0xffff0000, v7
	s_waitcnt vmcnt(14)
	v_and_b32_e32 v45, 0xffff0000, v8
	v_and_b32_e32 v47, 0xffff0000, v9
	v_lshlrev_b32_e32 v40, 16, v6
	v_lshlrev_b32_e32 v42, 16, v7
	v_lshlrev_b32_e32 v44, 16, v8
	v_lshlrev_b32_e32 v46, 16, v9
	s_waitcnt vmcnt(13)
	v_lshlrev_b32_e32 v48, 16, v10
	v_and_b32_e32 v49, 0xffff0000, v10
	v_lshlrev_b32_e32 v50, 16, v11
	v_and_b32_e32 v51, 0xffff0000, v11
	s_waitcnt vmcnt(11)
	v_lshlrev_b32_e32 v54, 16, v14
	v_and_b32_e32 v55, 0xffff0000, v14
	v_lshlrev_b32_e32 v56, 16, v15
	v_and_b32_e32 v57, 0xffff0000, v15
	s_waitcnt vmcnt(10)
	v_lshlrev_b32_e32 v58, 16, v16
	v_and_b32_e32 v59, 0xffff0000, v16
	v_lshlrev_b32_e32 v60, 16, v17
	v_and_b32_e32 v61, 0xffff0000, v17
	s_waitcnt vmcnt(9)
	v_lshlrev_b32_e32 v14, 16, v18
	v_and_b32_e32 v15, 0xffff0000, v18
	v_lshlrev_b32_e32 v10, 16, v19
	v_and_b32_e32 v11, 0xffff0000, v19
	v_mul_f32_e32 v16, v41, v41
	v_mul_f32_e32 v17, v43, v43
	v_mul_f32_e32 v18, v45, v45
	v_mul_f32_e32 v19, v47, v47
	v_lshlrev_b32_e32 v52, 16, v12
	v_and_b32_e32 v53, 0xffff0000, v12
	v_lshlrev_b32_e32 v12, 16, v13
	v_and_b32_e32 v13, 0xffff0000, v13
	s_waitcnt vmcnt(8)
	v_lshlrev_b32_e32 v8, 16, v20
	v_and_b32_e32 v9, 0xffff0000, v20
	v_lshlrev_b32_e32 v6, 16, v21
	v_and_b32_e32 v7, 0xffff0000, v21
	v_mul_f32_e32 v20, v49, v49
	v_mul_f32_e32 v21, v51, v51
	v_fmac_f32_e32 v16, v40, v40
	v_fmac_f32_e32 v17, v42, v42
	v_fmac_f32_e32 v18, v44, v44
	v_fmac_f32_e32 v19, v46, v46
	v_mul_f32_e32 v68, v53, v53
	v_mul_f32_e32 v69, v13, v13
	v_fmac_f32_e32 v20, v48, v48
	v_fmac_f32_e32 v21, v50, v50
	v_add_f32_e32 v16, v16, v17
	v_add_f32_e32 v17, v18, v19
	v_mul_f32_e32 v70, v55, v55
	v_mul_f32_e32 v71, v57, v57
	v_fmac_f32_e32 v68, v52, v52
	v_fmac_f32_e32 v69, v12, v12
	v_add_f32_e32 v18, v20, v21
	v_add_f32_e32 v16, v16, v17
	v_fmac_f32_e32 v70, v54, v54
	v_fmac_f32_e32 v71, v56, v56
	v_add_f32_e32 v19, v68, v69
	v_add_f32_e32 v16, v16, v18
	v_add_f32_e32 v16, v16, v19
	v_add_f32_e32 v17, v70, v71
	v_add_f32_e32 v16, v16, v17
	v_mul_f32_e32 v17, v59, v59
	v_mul_f32_e32 v18, v61, v61
	v_fmac_f32_e32 v17, v58, v58
	v_fmac_f32_e32 v18, v60, v60
	v_add_f32_e32 v17, v17, v18
	v_add_f32_e32 v16, v16, v17
	v_mul_f32_e32 v17, v15, v15
	v_mul_f32_e32 v18, v11, v11
	v_fmac_f32_e32 v17, v14, v14
	v_fmac_f32_e32 v18, v10, v10
	v_add_f32_e32 v17, v17, v18
	v_add_f32_e32 v16, v16, v17
	v_mul_f32_e32 v17, v9, v9
	v_mul_f32_e32 v18, v7, v7
	v_fmac_f32_e32 v17, v8, v8
	v_fmac_f32_e32 v18, v6, v6
	v_add_f32_e32 v17, v17, v18
	v_add_f32_e32 v16, v16, v17
	v_and_b32_e32 v17, 64, v39
	v_add_u32_e32 v17, 64, v17
	v_xor_b32_e32 v18, 1, v39
	v_cmp_lt_i32_e32 vcc, v18, v17
	s_waitcnt vmcnt(7)
	v_lshlrev_b32_e32 v62, 16, v22
	v_and_b32_e32 v63, 0xffff0000, v22
	v_cndmask_b32_e32 v18, v39, v18, vcc
	v_lshlrev_b32_e32 v91, 2, v18
	ds_bpermute_b32 v18, v91, v16
	v_lshlrev_b32_e32 v64, 16, v23
	v_and_b32_e32 v65, 0xffff0000, v23
	ds_read_b128 v[20:23], v97 offset:1024
	s_waitcnt vmcnt(4)
	v_lshlrev_b32_e32 v70, 16, v28
	s_waitcnt lgkmcnt(1)
	v_add_f32_e32 v16, v16, v18
	v_xor_b32_e32 v18, 2, v39
	v_cmp_lt_i32_e32 vcc, v18, v17
	v_and_b32_e32 v71, 0xffff0000, v28
	v_lshlrev_b32_e32 v72, 16, v29
	v_cndmask_b32_e32 v18, v39, v18, vcc
	v_lshlrev_b32_e32 v92, 2, v18
	ds_bpermute_b32 v18, v92, v16
	v_and_b32_e32 v73, 0xffff0000, v29
	v_lshlrev_b32_e32 v66, 16, v24
	v_and_b32_e32 v67, 0xffff0000, v24
	v_lshlrev_b32_e32 v24, 16, v25
	s_waitcnt lgkmcnt(0)
	v_add_f32_e32 v16, v16, v18
	v_xor_b32_e32 v18, 4, v39
	v_cmp_lt_i32_e32 vcc, v18, v17
	v_and_b32_e32 v25, 0xffff0000, v25
	s_waitcnt vmcnt(3)
	v_lshlrev_b32_e32 v74, 16, v30
	v_cndmask_b32_e32 v18, v39, v18, vcc
	v_lshlrev_b32_e32 v93, 2, v18
	ds_bpermute_b32 v18, v93, v16
	v_and_b32_e32 v75, 0xffff0000, v30
	v_lshlrev_b32_e32 v76, 16, v31
	v_and_b32_e32 v77, 0xffff0000, v31
	s_waitcnt vmcnt(0)
	v_lshlrev_b32_e32 v86, 16, v36
	s_waitcnt lgkmcnt(0)
	v_add_f32_e32 v16, v16, v18
	v_xor_b32_e32 v18, 8, v39
	v_cmp_lt_i32_e32 vcc, v18, v17
	v_and_b32_e32 v87, 0xffff0000, v36
	v_lshlrev_b32_e32 v88, 16, v37
	v_cndmask_b32_e32 v18, v39, v18, vcc
	v_lshlrev_b32_e32 v94, 2, v18
	ds_bpermute_b32 v18, v94, v16
	v_and_b32_e32 v89, 0xffff0000, v37
	v_lshlrev_b32_e32 v82, 16, v34
	v_and_b32_e32 v83, 0xffff0000, v34
	v_lshlrev_b32_e32 v84, 16, v35
	s_waitcnt lgkmcnt(0)
	v_add_f32_e32 v16, v16, v18
	v_xor_b32_e32 v18, 16, v39
	v_cmp_lt_i32_e32 vcc, v18, v17
	v_and_b32_e32 v85, 0xffff0000, v35
	v_lshlrev_b32_e32 v68, 16, v26
	v_cndmask_b32_e32 v18, v39, v18, vcc
	v_lshlrev_b32_e32 v95, 2, v18
	ds_bpermute_b32 v18, v95, v16
	v_and_b32_e32 v69, 0xffff0000, v26
	v_lshlrev_b32_e32 v26, 16, v27
	v_and_b32_e32 v27, 0xffff0000, v27
	v_lshlrev_b32_e32 v78, 16, v32
	s_waitcnt lgkmcnt(0)
	v_add_f32_e32 v16, v16, v18
	v_xor_b32_e32 v18, 32, v39
	v_cmp_lt_i32_e32 vcc, v18, v17
	v_and_b32_e32 v79, 0xffff0000, v32
	v_lshlrev_b32_e32 v80, 16, v33
	v_cndmask_b32_e32 v17, v39, v18, vcc
	v_lshlrev_b32_e32 v96, 2, v17
	ds_bpermute_b32 v17, v96, v16
	v_and_b32_e32 v81, 0xffff0000, v33
	s_waitcnt lgkmcnt(0)
	v_add_f32_e32 v16, v16, v17
	v_fmamk_f32 v16, v16, 0x3a000000, v38
	v_rsq_f32_e32 v90, v16
	ds_read_b128 v[16:19], v97
	v_pk_mul_f32 v[28:29], v[40:41], v[90:91] op_sel_hi:[1,0]
	v_pk_mul_f32 v[30:31], v[42:43], v[90:91] op_sel_hi:[1,0]
	s_waitcnt lgkmcnt(0)
	v_pk_fma_f32 v[36:37], v[16:17], v[28:29], v[62:63]
	v_pk_mul_f32 v[16:17], v[46:47], v[90:91] op_sel_hi:[1,0]
	v_pk_fma_f32 v[34:35], v[18:19], v[30:31], v[64:65]
	v_pk_fma_f32 v[28:29], v[22:23], v[16:17], v[24:25]
	ds_read_b128 v[16:19], v97 offset:2048
	ds_read_b128 v[22:25], v97 offset:3072
	v_pk_mul_f32 v[30:31], v[44:45], v[90:91] op_sel_hi:[1,0]
	v_pk_mul_f32 v[40:41], v[52:53], v[90:91] op_sel_hi:[1,0]
	v_pk_fma_f32 v[32:33], v[20:21], v[30:31], v[66:67]
	v_pk_mul_f32 v[20:21], v[48:49], v[90:91] op_sel_hi:[1,0]
	v_pk_mul_f32 v[30:31], v[50:51], v[90:91] op_sel_hi:[1,0]
	v_pk_mul_f32 v[12:13], v[12:13], v[90:91] op_sel_hi:[1,0]
	s_waitcnt lgkmcnt(1)
	v_pk_fma_f32 v[26:27], v[18:19], v[30:31], v[26:27]
	v_pk_fma_f32 v[30:31], v[16:17], v[20:21], v[68:69]
	ds_read_b128 v[16:19], v97 offset:4096
	s_waitcnt lgkmcnt(1)
	v_pk_fma_f32 v[20:21], v[24:25], v[12:13], v[72:73]
	v_pk_fma_f32 v[24:25], v[22:23], v[40:41], v[70:71]
	ds_read_b128 v[40:43], v97 offset:5120
	v_pk_mul_f32 v[12:13], v[54:55], v[90:91] op_sel_hi:[1,0]
	v_pk_mul_f32 v[22:23], v[56:57], v[90:91] op_sel_hi:[1,0]
	v_pk_mul_f32 v[14:15], v[90:91], v[14:15] op_sel_hi:[0,1]
	s_waitcnt lgkmcnt(1)
	v_pk_fma_f32 v[18:19], v[18:19], v[22:23], v[76:77]
	v_pk_fma_f32 v[22:23], v[16:17], v[12:13], v[74:75]
	v_pk_mul_f32 v[12:13], v[90:91], v[60:61] op_sel_hi:[0,1]
	s_waitcnt lgkmcnt(0)
	v_pk_fma_f32 v[12:13], v[42:43], v[12:13], v[80:81]
	ds_read_b128 v[42:45], v97 offset:6144
	ds_read_b128 v[46:49], v97 offset:7168
	v_pk_mul_f32 v[16:17], v[90:91], v[58:59] op_sel_hi:[0,1]
	v_pk_mul_f32 v[10:11], v[90:91], v[10:11] op_sel_hi:[0,1]
	v_pk_fma_f32 v[16:17], v[40:41], v[16:17], v[78:79]
	s_waitcnt lgkmcnt(1)
	v_pk_fma_f32 v[14:15], v[42:43], v[14:15], v[82:83]
	v_mov_b32_e32 v42, v37
	v_mov_b32_e32 v43, v33
	v_pk_fma_f32 v[10:11], v[44:45], v[10:11], v[84:85]
	v_mov_b32_e32 v40, v36
	v_mov_b32_e32 v41, v32
	v_pk_mul_f32 v[42:43], v[42:43], v[42:43]
	v_mov_b32_e32 v44, v35
	v_mov_b32_e32 v45, v29
	v_pk_fma_f32 v[40:41], v[40:41], v[40:41], v[42:43]
	v_mov_b32_e32 v42, v34
	v_mov_b32_e32 v43, v28
	v_pk_mul_f32 v[44:45], v[44:45], v[44:45]
	v_pk_mul_f32 v[8:9], v[90:91], v[8:9] op_sel_hi:[0,1]
	v_pk_fma_f32 v[42:43], v[42:43], v[42:43], v[44:45]
	v_pk_mul_f32 v[44:45], v[30:31], v[30:31]
	v_pk_add_f32 v[40:41], v[40:41], v[42:43]
	v_pk_mul_f32 v[42:43], v[26:27], v[26:27]
	v_pk_add_f32 v[40:41], v[40:41], v[40:41] op_sel_hi:[0,1]
	s_waitcnt lgkmcnt(0)
	v_pk_fma_f32 v[8:9], v[46:47], v[8:9], v[86:87]
	v_pk_mov_b32 v[46:47], v[44:45], v[42:43] op_sel:[1,0]
	v_mov_b32_e32 v45, v43
	v_mul_f32_e32 v40, v24, v24
	v_pk_add_f32 v[42:43], v[46:47], v[44:45]
	v_pk_fma_f32 v[44:45], v[24:25], v[24:25], v[40:41] op_sel_hi:[1,1,0]
	v_mul_f32_e32 v40, v20, v20
	v_pk_add_f32 v[42:43], v[42:43], v[42:43] op_sel_hi:[0,1]
	v_pk_fma_f32 v[46:47], v[20:21], v[20:21], v[40:41] op_sel_hi:[1,1,0]
	v_mul_f32_e32 v44, v22, v22
	v_mul_f32_e32 v46, v23, v23
	v_mul_f32_e32 v42, v18, v18
	v_mul_f32_e32 v40, v19, v19
	v_pk_add_f32 v[44:45], v[44:45], v[46:47]
	v_pk_add_f32 v[40:41], v[42:43], v[40:41]
	v_pk_mul_f32 v[42:43], v[12:13], v[12:13]
	v_pk_add_f32 v[40:41], v[44:45], v[40:41]
	v_pk_mul_f32 v[44:45], v[16:17], v[16:17]
	v_pk_add_f32 v[40:41], v[40:41], v[40:41] op_sel:[0,1] op_sel_hi:[1,0]
	v_pk_mov_b32 v[46:47], v[44:45], v[42:43] op_sel:[1,0]
	v_mov_b32_e32 v45, v43
	v_pk_add_f32 v[42:43], v[46:47], v[44:45]
	v_mul_f32_e32 v44, v8, v8
	v_mul_f32_e32 v45, v9, v9
	v_pk_add_f32 v[42:43], v[42:43], v[42:43] op_sel:[0,1] op_sel_hi:[1,0]
	v_pk_mul_f32 v[6:7], v[90:91], v[6:7] op_sel_hi:[0,1]
	v_mov_b32_e32 v43, v44
	v_mov_b32_e32 v41, v45
	v_pk_fma_f32 v[6:7], v[48:49], v[6:7], v[88:89]
	v_pk_add_f32 v[40:41], v[42:43], v[40:41]
	v_mul_f32_e32 v42, v15, v15
	v_mul_f32_e32 v44, v11, v11
	v_mul_f32_e32 v46, v6, v6
	v_mul_f32_e32 v47, v7, v7
	v_pk_fma_f32 v[42:43], v[14:15], v[14:15], v[42:43] op_sel_hi:[1,1,0]
	v_pk_fma_f32 v[44:45], v[10:11], v[10:11], v[44:45] op_sel_hi:[1,1,0]
	v_mov_b32_e32 v43, v46
	v_mov_b32_e32 v45, v47
	v_pk_add_f32 v[42:43], v[42:43], v[44:45]
	s_nop 0
	v_pk_add_f32 v[40:41], v[40:41], v[42:43]
	s_nop 0
	v_add_f32_e32 v42, v40, v41
	ds_bpermute_b32 v43, v91, v42
	v_cvt_pk_bf16_f32 v40, v36, v37
	v_cvt_pk_bf16_f32 v41, v34, v35
	global_store_dwordx2 v[4:5], v[40:41], off offset:-3584
	v_cvt_pk_bf16_f32 v40, v32, v33
	s_waitcnt lgkmcnt(0)
	v_add_f32_e32 v42, v42, v43
	ds_bpermute_b32 v43, v92, v42
	v_cvt_pk_bf16_f32 v41, v28, v29
	global_store_dwordx2 v[4:5], v[40:41], off offset:-3072
	v_cvt_pk_bf16_f32 v40, v30, v31
	v_cvt_pk_bf16_f32 v41, v26, v27
	s_waitcnt lgkmcnt(0)
	v_add_f32_e32 v42, v42, v43
	ds_bpermute_b32 v43, v93, v42
	global_store_dwordx2 v[4:5], v[40:41], off offset:-2560
	v_cvt_pk_bf16_f32 v40, v24, v25
	v_cvt_pk_bf16_f32 v41, v20, v21
	global_store_dwordx2 v[4:5], v[40:41], off offset:-2048
	s_waitcnt lgkmcnt(0)
	v_add_f32_e32 v42, v42, v43
	ds_bpermute_b32 v43, v94, v42
	v_cvt_pk_bf16_f32 v40, v22, v23
	v_cvt_pk_bf16_f32 v41, v18, v19
	global_store_dwordx2 v[4:5], v[40:41], off offset:-1536
	v_cvt_pk_bf16_f32 v40, v16, v17
	s_waitcnt lgkmcnt(0)
	v_add_f32_e32 v42, v42, v43
	ds_bpermute_b32 v43, v95, v42
	v_cvt_pk_bf16_f32 v41, v12, v13
	global_store_dwordx2 v[4:5], v[40:41], off offset:-1024
	v_cvt_pk_bf16_f32 v40, v14, v15
	v_cvt_pk_bf16_f32 v41, v10, v11
	s_waitcnt lgkmcnt(0)
	v_add_f32_e32 v42, v42, v43
	ds_bpermute_b32 v43, v96, v42
	global_store_dwordx2 v[4:5], v[40:41], off offset:-512
	v_cvt_pk_bf16_f32 v48, v8, v9
	v_cvt_pk_bf16_f32 v49, v6, v7
	s_waitcnt lgkmcnt(0)
	v_add_f32_e32 v40, v42, v43
	v_fmamk_f32 v40, v40, 0x3a000000, v38
	v_rsq_f32_e32 v50, v40
	ds_read_b128 v[40:43], v97 offset:8192
	ds_read_b128 v[44:47], v97 offset:16384
	global_store_dwordx2 v[4:5], v[48:49], off
	v_pk_mul_f32 v[4:5], v[36:37], v[50:51] op_sel_hi:[1,0]
	v_pk_mul_f32 v[34:35], v[34:35], v[50:51] op_sel_hi:[1,0]
	s_waitcnt lgkmcnt(0)
	v_pk_fma_f32 v[4:5], v[40:41], v[4:5], v[44:45]
	v_pk_fma_f32 v[34:35], v[42:43], v[34:35], v[46:47]
	v_cvt_pk_bf16_f32 v4, v4, v5
	v_add_co_u32_e32 v44, vcc, s1, v2
	v_cvt_pk_bf16_f32 v5, v34, v35
	ds_read_b128 v[34:37], v97 offset:9216
	ds_read_b128 v[40:43], v97 offset:17408
	v_addc_co_u32_e32 v45, vcc, -1, v3, vcc
	global_store_dwordx2 v[44:45], v[4:5], off offset:-3584
	v_pk_mul_f32 v[4:5], v[32:33], v[50:51] op_sel_hi:[1,0]
	v_pk_mul_f32 v[28:29], v[28:29], v[50:51] op_sel_hi:[1,0]
	s_waitcnt lgkmcnt(0)
	v_pk_fma_f32 v[4:5], v[34:35], v[4:5], v[40:41]
	v_pk_fma_f32 v[28:29], v[36:37], v[28:29], v[42:43]
	v_cvt_pk_bf16_f32 v4, v4, v5
	v_pk_mul_f32 v[26:27], v[26:27], v[50:51] op_sel_hi:[1,0]
	v_cvt_pk_bf16_f32 v5, v28, v29
	ds_read_b128 v[32:35], v97 offset:10240
	ds_read_b128 v[40:43], v97 offset:18432
	global_store_dwordx2 v[44:45], v[4:5], off offset:-3072
	v_pk_mul_f32 v[4:5], v[30:31], v[50:51] op_sel_hi:[1,0]
	v_pk_mul_f32 v[20:21], v[20:21], v[50:51] op_sel_hi:[1,0]
	v_pk_mul_f32 v[18:19], v[18:19], v[50:51] op_sel_hi:[1,0]
	s_waitcnt lgkmcnt(0)
	v_pk_fma_f32 v[26:27], v[26:27], v[34:35], v[42:43]
	v_pk_fma_f32 v[4:5], v[4:5], v[32:33], v[40:41]
	v_pk_mul_f32 v[12:13], v[12:13], v[50:51] op_sel_hi:[1,0]
	v_cvt_pk_bf16_f32 v4, v4, v5
	v_cvt_pk_bf16_f32 v5, v26, v27
	ds_read_b128 v[26:29], v97 offset:11264
	ds_read_b128 v[30:33], v97 offset:19456
	global_store_dwordx2 v[44:45], v[4:5], off offset:-2560
	v_pk_mul_f32 v[4:5], v[24:25], v[50:51] op_sel_hi:[1,0]
	v_pk_mul_f32 v[10:11], v[10:11], v[50:51] op_sel_hi:[1,0]
	v_pk_mul_f32 v[6:7], v[6:7], v[50:51] op_sel_hi:[1,0]
	s_waitcnt lgkmcnt(0)
	v_pk_fma_f32 v[4:5], v[4:5], v[26:27], v[30:31]
	v_pk_fma_f32 v[20:21], v[20:21], v[28:29], v[32:33]
	v_cvt_pk_bf16_f32 v4, v4, v5
	s_nop 0
	v_cvt_pk_bf16_f32 v5, v20, v21
	ds_read_b128 v[24:27], v97 offset:12288
	ds_read_b128 v[28:31], v97 offset:20480
	global_store_dwordx2 v[44:45], v[4:5], off offset:-2048
	v_pk_mul_f32 v[4:5], v[22:23], v[50:51] op_sel_hi:[1,0]
	s_waitcnt lgkmcnt(0)
	v_pk_fma_f32 v[18:19], v[18:19], v[26:27], v[30:31]
	v_pk_fma_f32 v[4:5], v[4:5], v[24:25], v[28:29]
	s_nop 0
	v_cvt_pk_bf16_f32 v4, v4, v5
	v_cvt_pk_bf16_f32 v5, v18, v19
	ds_read_b128 v[18:21], v97 offset:13312
	ds_read_b128 v[22:25], v97 offset:21504
	global_store_dwordx2 v[44:45], v[4:5], off offset:-1536
	v_pk_mul_f32 v[4:5], v[16:17], v[50:51] op_sel_hi:[1,0]
	s_waitcnt lgkmcnt(0)
	v_pk_fma_f32 v[12:13], v[12:13], v[20:21], v[24:25]
	v_pk_fma_f32 v[4:5], v[4:5], v[18:19], v[22:23]
	s_nop 0
	v_cvt_pk_bf16_f32 v4, v4, v5
	v_cvt_pk_bf16_f32 v5, v12, v13
	ds_read_b128 v[16:19], v97 offset:14336
	ds_read_b128 v[20:23], v97 offset:22528
	global_store_dwordx2 v[44:45], v[4:5], off offset:-1024
	v_pk_mul_f32 v[4:5], v[14:15], v[50:51] op_sel_hi:[1,0]
	s_waitcnt lgkmcnt(0)
	v_pk_fma_f32 v[10:11], v[10:11], v[18:19], v[22:23]
	v_pk_fma_f32 v[4:5], v[4:5], v[16:17], v[20:21]
	s_nop 0
	v_cvt_pk_bf16_f32 v4, v4, v5
	v_cvt_pk_bf16_f32 v5, v10, v11
	ds_read_b128 v[10:13], v97 offset:15360
	ds_read_b128 v[14:17], v97 offset:23552
	global_store_dwordx2 v[44:45], v[4:5], off offset:-512
	v_pk_mul_f32 v[4:5], v[8:9], v[50:51] op_sel_hi:[1,0]
	s_waitcnt lgkmcnt(0)
	v_pk_fma_f32 v[6:7], v[6:7], v[12:13], v[16:17]
	v_pk_fma_f32 v[4:5], v[4:5], v[10:11], v[14:15]
	s_nop 0
	v_cvt_pk_bf16_f32 v4, v4, v5
	v_cvt_pk_bf16_f32 v5, v6, v7
	global_store_dwordx2 v[44:45], v[4:5], off
	s_branch .LBB0_3124

.LBB0_3335:
	s_cmp_lt_i32 s84, 33
	s_cselect_b64 s[0:1], -1, 0
	s_cmp_gt_i32 s85, 32
	s_cselect_b64 s[2:3], -1, 0
	s_and_b64 s[0:1], s[0:1], s[2:3]
	s_andn2_b64 vcc, exec, s[0:1]
	s_cbranch_vccnz .LBB0_3395
	v_mov_b32_e32 v181, 0
	v_lshl_add_u64 v[0:1], s[48:49], 0, v[180:181]
	v_add_co_u32_e32 v0, vcc, 0x1e000, v0
	v_lshl_add_u64 v[20:21], s[88:89], 0, v[180:181]
	s_nop 0
	v_addc_co_u32_e32 v1, vcc, 0, v1, vcc
	v_add_co_u32_e32 v12, vcc, 0x9be000, v20
	global_load_dwordx4 v[0:3], v[0:1], off nt
	s_nop 0
	v_addc_co_u32_e32 v13, vcc, 0, v21, vcc
	v_add_co_u32_e32 v14, vcc, 0x9ca000, v20
	v_readlane_b32 s0, v250, 44
	s_nop 0
	v_addc_co_u32_e32 v15, vcc, 0, v21, vcc
	v_add_co_u32_e32 v22, vcc, 0x9d6000, v20
	s_waitcnt lgkmcnt(0)
	global_load_dwordx4 v[4:7], v[12:13], off nt
	global_load_dwordx4 v[8:11], v[14:15], off nt
	v_addc_co_u32_e32 v23, vcc, 0, v21, vcc
	v_add_co_u32_e32 v24, vcc, 0x9e2000, v20
	s_lshl_b32 s0, s0, 3
	s_nop 0
	v_addc_co_u32_e32 v25, vcc, 0, v21, vcc
	v_add_co_u32_e32 v20, vcc, 0x9ee000, v20
	global_load_dwordx4 v[12:15], v[22:23], off nt
	global_load_dwordx4 v[16:19], v[24:25], off nt
	v_addc_co_u32_e32 v21, vcc, 0, v21, vcc
	global_load_dwordx4 v[20:23], v[20:21], off nt
	v_add_u32_e32 v24, 0, v180
	v_readlane_b32 s2, v250, 21
	s_add_i32 s2, s0, s2
	s_mov_b32 s1, 0
	v_add_u32_e32 v25, 0x12000, v24
	v_add_u32_e32 v26, 0x18000, v24
	s_cmpk_gt_i32 s2, 0x43ff
	s_waitcnt vmcnt(0)
	v_pk_mul_f32 v[6:7], v[2:3], v[6:7]
	v_pk_mul_f32 v[4:5], v[0:1], v[4:5]
	ds_write_b128 v24, v[4:7]
	v_pk_mul_f32 v[6:7], v[2:3], v[10:11]
	v_pk_mul_f32 v[4:5], v[0:1], v[8:9]
	ds_write_b128 v24, v[4:7] offset:24576
	v_pk_mul_f32 v[6:7], v[2:3], v[14:15]
	v_pk_mul_f32 v[4:5], v[0:1], v[12:13]
	ds_write_b128 v24, v[4:7] offset:49152
	v_pk_mul_f32 v[6:7], v[2:3], v[18:19]
	v_pk_mul_f32 v[4:5], v[0:1], v[16:17]
	v_pk_mul_f32 v[2:3], v[2:3], v[22:23]
	v_pk_mul_f32 v[0:1], v[0:1], v[20:21]
	ds_write_b128 v25, v[4:7]
	ds_write_b128 v26, v[0:3]
	s_waitcnt lgkmcnt(0)
	s_barrier
	s_cbranch_scc1 .LBB0_3341
	s_ashr_i32 s3, s2, 31
	s_lshl_b32 s4, s61, 3
	s_lshl_b64 s[6:7], s[2:3], 12
	s_add_u32 s6, s88, s6
	v_or_b32_e32 v2, 0x100, v178
	v_lshlrev_b32_e32 v180, 3, v178
	s_addc_u32 s7, s89, s7
	v_or_b32_e32 v4, 0x140, v178
	v_or_b32_e32 v6, 0x180, v178
	v_or_b32_e32 v8, 0x1c0, v178
	v_lshl_add_u64 v[0:1], s[6:7], 0, v[180:181]
	s_mov_b64 s[6:7], 0x24900e00
	s_ashr_i32 s5, s4, 31
	v_lshlrev_b32_e32 v13, 4, v2
	v_mbcnt_lo_u32_b32 v2, -1, 0
	v_lshl_add_u32 v10, v178, 4, 0
	v_lshl_add_u64 v[0:1], v[0:1], 0, s[6:7]
	s_lshl_b64 s[6:7], s[4:5], 12
	v_mov_b32_e32 v11, 0x358637bd
	v_lshlrev_b32_e32 v12, 4, v178
	v_lshlrev_b32_e32 v14, 4, v4
	v_lshlrev_b32_e32 v15, 4, v6
	v_lshlrev_b32_e32 v16, 4, v8
	v_mbcnt_hi_u32_b32 v17, -1, v2
	s_branch .LBB0_3339

.LBB0_3339:
	s_mul_hi_i32 s0, s2, 0x78787879
	s_lshr_b32 s3, s0, 31
	s_ashr_i32 s0, s0, 11
	s_add_i32 s8, s0, s3
	s_mul_i32 s0, s8, 0xffffef00
	s_add_i32 s0, s2, s0
	s_cmpk_lt_i32 s0, 0x100
	s_cbranch_scc1 .LBB0_3338
	global_load_dwordx2 v[2:3], v[0:1], off offset:-3584 nt
	global_load_dwordx2 v[4:5], v[0:1], off offset:-3072 nt
	global_load_dwordx2 v[6:7], v[0:1], off offset:-2560 nt
	global_load_dwordx2 v[8:9], v[0:1], off offset:-2048 nt
	global_load_dwordx2 v[18:19], v[0:1], off offset:-1536 nt
	global_load_dwordx2 v[20:21], v[0:1], off offset:-1024 nt
	global_load_dwordx2 v[22:23], v[0:1], off offset:-512 nt
	global_load_dwordx2 v[24:25], v[0:1], off nt
	v_add_co_u32_e32 v26, vcc, 0xf3400000, v0
	s_mul_i32 s3, s8, 0x6000
	s_nop 0
	v_addc_co_u32_e32 v27, vcc, -1, v1, vcc
	global_load_dwordx2 v[28:29], v[26:27], off offset:-3584 nt
	global_load_dwordx2 v[30:31], v[26:27], off offset:-3072 nt
	global_load_dwordx2 v[32:33], v[26:27], off offset:-2560 nt
	global_load_dwordx2 v[34:35], v[26:27], off offset:-2048 nt
	global_load_dwordx2 v[36:37], v[26:27], off offset:-1536 nt
	global_load_dwordx2 v[38:39], v[26:27], off offset:-1024 nt
	global_load_dwordx2 v[40:41], v[26:27], off offset:-512 nt
	global_load_dwordx2 v[42:43], v[26:27], off nt
	v_add_u32_e32 v93, s3, v10
	s_ashr_i32 s9, s8, 31
	s_addk_i32 s0, 0xff00
	s_lshl_b64 s[8:9], s[8:9], 25
	s_add_u32 s3, s62, s8
	s_addc_u32 s5, s63, s9
	s_lshl_b64 s[8:9], s[0:1], 13
	s_add_u32 s8, s3, s8
	s_addc_u32 s9, s5, s9
	s_waitcnt vmcnt(15)
	v_and_b32_e32 v27, 0xffff0000, v2
	v_and_b32_e32 v45, 0xffff0000, v3
	s_waitcnt vmcnt(14)
	v_and_b32_e32 v47, 0xffff0000, v4
	v_and_b32_e32 v49, 0xffff0000, v5
	v_lshlrev_b32_e32 v26, 16, v2
	v_lshlrev_b32_e32 v44, 16, v3
	v_lshlrev_b32_e32 v46, 16, v4
	v_lshlrev_b32_e32 v48, 16, v5
	s_waitcnt vmcnt(13)
	v_and_b32_e32 v51, 0xffff0000, v6
	v_and_b32_e32 v53, 0xffff0000, v7
	s_waitcnt vmcnt(11)
	v_lshlrev_b32_e32 v58, 16, v18
	v_and_b32_e32 v59, 0xffff0000, v18
	v_lshlrev_b32_e32 v60, 16, v19
	v_and_b32_e32 v61, 0xffff0000, v19
	s_waitcnt vmcnt(10)
	v_lshlrev_b32_e32 v62, 16, v20
	v_and_b32_e32 v63, 0xffff0000, v20
	v_lshlrev_b32_e32 v64, 16, v21
	v_and_b32_e32 v65, 0xffff0000, v21
	v_mul_f32_e32 v18, v27, v27
	v_mul_f32_e32 v19, v45, v45
	v_mul_f32_e32 v20, v47, v47
	v_mul_f32_e32 v21, v49, v49
	v_lshlrev_b32_e32 v50, 16, v6
	v_lshlrev_b32_e32 v52, 16, v7
	v_lshlrev_b32_e32 v54, 16, v8
	v_and_b32_e32 v55, 0xffff0000, v8
	v_lshlrev_b32_e32 v56, 16, v9
	v_and_b32_e32 v57, 0xffff0000, v9
	s_waitcnt vmcnt(9)
	v_lshlrev_b32_e32 v8, 16, v22
	v_and_b32_e32 v9, 0xffff0000, v22
	v_lshlrev_b32_e32 v6, 16, v23
	v_and_b32_e32 v7, 0xffff0000, v23
	v_mul_f32_e32 v22, v51, v51
	v_mul_f32_e32 v23, v53, v53
	v_fmac_f32_e32 v18, v26, v26
	v_fmac_f32_e32 v19, v44, v44
	v_fmac_f32_e32 v20, v46, v46
	v_fmac_f32_e32 v21, v48, v48
	s_waitcnt vmcnt(8)
	v_lshlrev_b32_e32 v4, 16, v24
	v_and_b32_e32 v5, 0xffff0000, v24
	v_lshlrev_b32_e32 v2, 16, v25
	v_and_b32_e32 v3, 0xffff0000, v25
	v_mul_f32_e32 v24, v55, v55
	v_mul_f32_e32 v25, v57, v57
	v_fmac_f32_e32 v22, v50, v50
	v_fmac_f32_e32 v23, v52, v52
	v_add_f32_e32 v18, v18, v19
	v_add_f32_e32 v19, v20, v21
	v_mul_f32_e32 v70, v59, v59
	v_mul_f32_e32 v71, v61, v61
	v_fmac_f32_e32 v24, v54, v54
	v_fmac_f32_e32 v25, v56, v56
	v_add_f32_e32 v20, v22, v23
	v_add_f32_e32 v18, v18, v19
	v_fmac_f32_e32 v70, v58, v58
	v_fmac_f32_e32 v71, v60, v60
	v_add_f32_e32 v21, v24, v25
	v_add_f32_e32 v18, v18, v20
	v_add_f32_e32 v18, v18, v21
	v_add_f32_e32 v19, v70, v71
	v_add_f32_e32 v18, v18, v19
	v_mul_f32_e32 v19, v63, v63
	v_mul_f32_e32 v20, v65, v65
	v_fmac_f32_e32 v19, v62, v62
	v_fmac_f32_e32 v20, v64, v64
	v_add_f32_e32 v19, v19, v20
	v_add_f32_e32 v18, v18, v19
	v_mul_f32_e32 v19, v9, v9
	v_mul_f32_e32 v20, v7, v7
	v_fmac_f32_e32 v19, v8, v8
	v_fmac_f32_e32 v20, v6, v6
	v_add_f32_e32 v19, v19, v20
	v_add_f32_e32 v18, v18, v19
	v_mul_f32_e32 v19, v5, v5
	v_mul_f32_e32 v20, v3, v3
	v_fmac_f32_e32 v19, v4, v4
	v_fmac_f32_e32 v20, v2, v2
	v_add_f32_e32 v19, v19, v20
	v_add_f32_e32 v18, v18, v19
	v_and_b32_e32 v19, 64, v17
	v_add_u32_e32 v19, 64, v19
	v_xor_b32_e32 v20, 1, v17
	v_cmp_lt_i32_e32 vcc, v20, v19
	ds_read_b128 v[22:25], v93 offset:1024
	s_waitcnt vmcnt(7)
	v_lshlrev_b32_e32 v66, 16, v28
	v_cndmask_b32_e32 v20, v17, v20, vcc
	v_lshlrev_b32_e32 v20, 2, v20
	ds_bpermute_b32 v20, v20, v18
	v_and_b32_e32 v67, 0xffff0000, v28
	v_lshlrev_b32_e32 v28, 16, v29
	v_and_b32_e32 v29, 0xffff0000, v29
	s_waitcnt vmcnt(6)
	v_lshlrev_b32_e32 v68, 16, v30
	s_waitcnt lgkmcnt(0)
	v_add_f32_e32 v18, v18, v20
	v_xor_b32_e32 v20, 2, v17
	v_cmp_lt_i32_e32 vcc, v20, v19
	v_and_b32_e32 v69, 0xffff0000, v30
	v_lshlrev_b32_e32 v30, 16, v31
	v_cndmask_b32_e32 v20, v17, v20, vcc
	v_lshlrev_b32_e32 v20, 2, v20
	ds_bpermute_b32 v20, v20, v18
	v_and_b32_e32 v31, 0xffff0000, v31
	s_waitcnt vmcnt(5)
	v_lshlrev_b32_e32 v70, 16, v32
	v_and_b32_e32 v71, 0xffff0000, v32
	v_lshlrev_b32_e32 v72, 16, v33
	s_waitcnt lgkmcnt(0)
	v_add_f32_e32 v18, v18, v20
	v_xor_b32_e32 v20, 4, v17
	v_cmp_lt_i32_e32 vcc, v20, v19
	v_and_b32_e32 v73, 0xffff0000, v33
	s_waitcnt vmcnt(3)
	v_lshlrev_b32_e32 v76, 16, v36
	v_cndmask_b32_e32 v20, v17, v20, vcc
	v_lshlrev_b32_e32 v20, 2, v20
	ds_bpermute_b32 v20, v20, v18
	v_and_b32_e32 v77, 0xffff0000, v36
	v_lshlrev_b32_e32 v78, 16, v37
	v_and_b32_e32 v79, 0xffff0000, v37
	v_lshlrev_b32_e32 v74, 16, v34
	s_waitcnt lgkmcnt(0)
	v_add_f32_e32 v18, v18, v20
	v_xor_b32_e32 v20, 8, v17
	v_cmp_lt_i32_e32 vcc, v20, v19
	v_and_b32_e32 v75, 0xffff0000, v34
	v_lshlrev_b32_e32 v34, 16, v35
	v_cndmask_b32_e32 v20, v17, v20, vcc
	v_lshlrev_b32_e32 v20, 2, v20
	ds_bpermute_b32 v20, v20, v18
	v_and_b32_e32 v35, 0xffff0000, v35
	s_waitcnt vmcnt(2)
	v_lshlrev_b32_e32 v80, 16, v38
	v_and_b32_e32 v81, 0xffff0000, v38
	v_lshlrev_b32_e32 v82, 16, v39
	s_waitcnt lgkmcnt(0)
	v_add_f32_e32 v18, v18, v20
	v_xor_b32_e32 v20, 16, v17
	v_cmp_lt_i32_e32 vcc, v20, v19
	v_and_b32_e32 v83, 0xffff0000, v39
	s_waitcnt vmcnt(1)
	v_lshlrev_b32_e32 v84, 16, v40
	v_cndmask_b32_e32 v20, v17, v20, vcc
	v_lshlrev_b32_e32 v20, 2, v20
	ds_bpermute_b32 v20, v20, v18
	v_and_b32_e32 v85, 0xffff0000, v40
	v_lshlrev_b32_e32 v86, 16, v41
	v_and_b32_e32 v87, 0xffff0000, v41
	s_waitcnt vmcnt(0)
	v_lshlrev_b32_e32 v88, 16, v42
	s_waitcnt lgkmcnt(0)
	v_add_f32_e32 v18, v18, v20
	v_xor_b32_e32 v20, 32, v17
	v_cmp_lt_i32_e32 vcc, v20, v19
	v_and_b32_e32 v89, 0xffff0000, v42
	v_lshlrev_b32_e32 v90, 16, v43
	v_cndmask_b32_e32 v19, v17, v20, vcc
	v_lshlrev_b32_e32 v19, 2, v19
	ds_bpermute_b32 v19, v19, v18
	v_and_b32_e32 v91, 0xffff0000, v43
	s_waitcnt lgkmcnt(0)
	v_add_f32_e32 v18, v18, v19
	v_fmamk_f32 v18, v18, 0x3a000000, v11
	v_rsq_f32_e32 v92, v18
	ds_read_b128 v[18:21], v93
	v_pk_mul_f32 v[26:27], v[92:93], v[26:27] op_sel_hi:[0,1]
	v_pk_mul_f32 v[32:33], v[92:93], v[44:45] op_sel_hi:[0,1]
	s_waitcnt lgkmcnt(0)
	v_pk_fma_f32 v[18:19], v[18:19], v[26:27], v[66:67]
	v_pk_mul_f32 v[26:27], v[92:93], v[48:49] op_sel_hi:[0,1]
	v_pk_fma_f32 v[20:21], v[20:21], v[32:33], v[28:29]
	v_pk_mul_f32 v[32:33], v[92:93], v[46:47] op_sel_hi:[0,1]
	v_pk_fma_f32 v[24:25], v[24:25], v[26:27], v[30:31]
	ds_read_b128 v[26:29], v93 offset:2048
	v_pk_fma_f32 v[22:23], v[22:23], v[32:33], v[68:69]
	ds_read_b128 v[30:33], v93 offset:3072
	v_pk_mul_f32 v[36:37], v[92:93], v[50:51] op_sel_hi:[0,1]
	v_pk_mul_f32 v[38:39], v[92:93], v[52:53] op_sel_hi:[0,1]
	s_waitcnt lgkmcnt(1)
	v_pk_fma_f32 v[26:27], v[26:27], v[36:37], v[70:71]
	v_pk_mul_f32 v[36:37], v[92:93], v[56:57] op_sel_hi:[0,1]
	v_pk_fma_f32 v[28:29], v[28:29], v[38:39], v[72:73]
	v_pk_mul_f32 v[38:39], v[92:93], v[54:55] op_sel_hi:[0,1]
	s_waitcnt lgkmcnt(0)
	v_pk_fma_f32 v[32:33], v[32:33], v[36:37], v[34:35]
	ds_read_b128 v[34:37], v93 offset:4096
	v_pk_fma_f32 v[30:31], v[30:31], v[38:39], v[74:75]
	ds_read_b128 v[38:41], v93 offset:5120
	v_pk_mul_f32 v[42:43], v[92:93], v[58:59] op_sel_hi:[0,1]
	v_pk_mul_f32 v[44:45], v[92:93], v[60:61] op_sel_hi:[0,1]
	s_waitcnt lgkmcnt(1)
	v_pk_fma_f32 v[34:35], v[34:35], v[42:43], v[76:77]
	v_pk_mul_f32 v[42:43], v[92:93], v[64:65] op_sel_hi:[0,1]
	v_pk_fma_f32 v[36:37], v[36:37], v[44:45], v[78:79]
	v_pk_mul_f32 v[46:47], v[92:93], v[62:63] op_sel_hi:[0,1]
	s_waitcnt lgkmcnt(0)
	v_pk_fma_f32 v[40:41], v[40:41], v[42:43], v[82:83]
	ds_read_b128 v[42:45], v93 offset:6144
	v_pk_fma_f32 v[38:39], v[38:39], v[46:47], v[80:81]
	v_pk_mul_f32 v[46:47], v[92:93], v[8:9] op_sel_hi:[0,1]
	v_pk_mul_f32 v[48:49], v[92:93], v[6:7] op_sel_hi:[0,1]
	ds_read_b128 v[6:9], v93 offset:7168
	s_waitcnt lgkmcnt(1)
	v_pk_fma_f32 v[42:43], v[42:43], v[46:47], v[84:85]
	v_pk_mul_f32 v[46:47], v[92:93], v[4:5] op_sel_hi:[0,1]
	v_pk_mul_f32 v[2:3], v[92:93], v[2:3] op_sel_hi:[0,1]
	v_pk_fma_f32 v[44:45], v[44:45], v[48:49], v[86:87]
	s_waitcnt lgkmcnt(0)
	v_pk_fma_f32 v[4:5], v[8:9], v[2:3], v[90:91]
	v_pk_fma_f32 v[2:3], v[6:7], v[46:47], v[88:89]
	global_store_dwordx4 v12, v[18:21], s[8:9]
	global_store_dwordx4 v12, v[22:25], s[8:9] offset:1024
	global_store_dwordx4 v12, v[26:29], s[8:9] offset:2048
	global_store_dwordx4 v12, v[30:33], s[8:9] offset:3072
	global_store_dwordx4 v13, v[34:37], s[8:9]
	global_store_dwordx4 v14, v[38:41], s[8:9]
	global_store_dwordx4 v15, v[42:45], s[8:9]
	global_store_dwordx4 v16, v[2:5], s[8:9]
	s_branch .LBB0_3338
